# v72 + 7 row-panel-local phase transitions (pool GEMM/O-proj/w_out -> MLP-up -> MLP-down -> w_in on latent layers) synchronise only the 4 workgroups owning the 256-row panel, with the L1 invalidate iss
# speedup vs baseline: 1.0230x; 1.0119x over previous
; #define LAS __attribute__((address_space(3)))
; __device__ __forceinline__ unsigned xb_add(unsigned* p, unsigned v) { return __hip_atomic_fetch_add(p, v, __ATOMIC_RELAXED, __HIP_MEMORY_SCOPE_AGENT); }
; __device__ __forceinline__ unsigned xb_xcc_id() { return (unsigned)__builtin_amdgcn_s_getreg((3 << 11) | 20) & 0xFu; }
; __device__ __forceinline__ XcdBarrier xcd_barrier_post(unsigned* bar, volatile LAS unsigned* st, int tid) {
;     XcdBarrier b; b.bar = bar; b.x = xb_xcc_id(); b.st = st;
;     if (tid == 0) (void)xb_add(&bar[XB_XCNT(b.x)], 1u);
;     return b;
; __global__ void __launch_bounds__(NWAVES * 64, 2) fwd_kernel(Args args) {
;     ...
;     const int lo = args.ph_lo, hi = args.ph_hi;
;     int ph = 0;
;     if (tid0 < 2) ((volatile LAS unsigned*)(L + LDS_BARST))[tid0] = 0u;
;     __syncthreads();
;     XcdBarrier xbar = xcd_barrier_post((unsigned*)(A_->ws + WS_BAR), (volatile LAS unsigned*)(L + LDS_BARST), tid0);
_Z10fwd_kernel4Args:
	s_mov_b64 s[94:95], s[0:1]
	s_load_dwordx4 s[80:83], s[0:1], 0xc0
	s_load_dword s17, s[0:1], 0xd0
	s_add_u32 s0, s94, 0xc8
	s_addc_u32 s1, s95, 0
	v_and_b32_e32 v215, 0x3ff, v0
	v_writelane_b32 v254, s0, 0
	s_mov_b32 s84, s2
	v_cmp_gt_u32_e32 vcc, 2, v215
	v_writelane_b32 v254, s1, 1
	s_mov_b32 s98, 0
	v_writelane_b32 v255, s98, 59
	s_and_saveexec_b64 s[0:1], vcc
	v_lshl_add_u32 v1, v215, 2, 0
	v_add_u32_e32 v1, 0x23fc0, v1
	v_mov_b32_e32 v2, 0
	ds_write_b32 v1, v2
	s_or_b64 exec, exec, s[0:1]
	s_waitcnt lgkmcnt(0)
	s_barrier
	s_load_dwordx2 s[0:1], s[94:95], 0xb8
	s_getreg_b32 s4, hwreg(HW_REG_XCC_ID, 0, 4)
	v_cmp_eq_u32_e32 vcc, 0, v215
	s_waitcnt lgkmcnt(0)
	s_add_u32 s2, s0, 0xe0000
	s_addc_u32 s3, s1, 0
	s_and_b32 s16, s4, 15
	s_and_saveexec_b64 s[4:5], vcc
	s_cbranch_execz .LBB0_5
	s_mov_b64 s[6:7], exec
	v_mbcnt_lo_u32_b32 v1, s6, 0
	v_mbcnt_hi_u32_b32 v1, s7, v1
	v_cmp_eq_u32_e32 vcc, 0, v1
	s_and_b64 s[8:9], exec, vcc
	s_mov_b64 exec, s[8:9]
	s_cbranch_execz .LBB0_5
	s_lshl_b32 s8, s16, 8
	s_bcnt1_i32_b64 s6, s[6:7]
	v_mov_b32_e32 v1, s8
	v_mov_b32_e32 v2, s6
	global_atomic_add v1, v2, s[2:3] offset:1024

;     __device__ __forceinline__ void operator()(const f32x4 (&acc)[2][2][4][2], const Unit& u, int wr, int wc, int fr, int fq) const {
;     ...
;         const int rowt = u.pm * BM, b = rowt >= MLAT ? 2 : (rowt >> 13);
;         const float* gp = gate + b * 6144; const int col0 = u.pn * BM + wc * 32 + 8 * fq;
;         f32x4 gv[2][2], wv[2][2];
; #pragma unroll
;         for (int bj = 0; bj < 2; ++bj)
; #pragma unroll
;             for (int n = 0; n < 2; ++n) { gv[bj][n] = *(const f32x4*)(gp + col0 + bj * HALF + n * 4); if (cs) gv[bj][n] = gv[bj][n] * *(const f32x4*)(cs + col0 + bj * HALF + n * 4);
;                 if (hb) wv[bj][n] = *(const f32x4*)(wn_g + col0 + bj * HALF + n * 4) * (*(const f32x4*)(wn_sc + b * 6144 + col0 + bj * HALF + n * 4) + 1.0f); }
;         const float* bb = base_lat ? (rowt >= MLAT ? base_ctx + (size_t)(rowt - MLAT) * DM : base_lat + (size_t)rowt * DM) : nullptr;
; #pragma unroll
;         for (int ai = 0; ai < 2; ++ai) {
;             u32x4 raw[4][2];
; #pragma unroll
;             for (int m = 0; m < 4; ++m)
; #pragma unroll
;                 for (int bj = 0; bj < 2; ++bj) raw[m][bj] = *(const u32x4*)(h16 + (size_t)rowt * DM + (size_t)(wr * 64 + fr + ai * HALF + m * 16) * DM + col0 + bj * HALF);
; #pragma unroll
;             for (int m = 0; m < 4; ++m) { const int rl = wr * 64 + fr + ai * HALF + m * 16; const size_t off = (size_t)rl * DM + col0; float sq = 0.f;
;                 bf16_t* hrow = h16 + (size_t)rowt * DM + off;
; #pragma unroll
;                 for (int bj = 0; bj < 2; ++bj) { f32x4 b0, b1;
;                     if (bb) { b0 = *(const f32x4*)(bb + off + bj * HALF); b1 = *(const f32x4*)(bb + off + bj * HALF + 4); }
;                     else { const u32x4 r = raw[m][bj];
;                         b0 = (f32x4){__uint_as_float(r.x << 16), __uint_as_float(r.x & 0xffff0000u), __uint_as_float(r.y << 16), __uint_as_float(r.y & 0xffff0000u)};
;                         b1 = (f32x4){__uint_as_float(r.z << 16), __uint_as_float(r.z & 0xffff0000u), __uint_as_float(r.w << 16), __uint_as_float(r.w & 0xffff0000u)}; }
;                     const f32x4 o0 = b0 + gv[bj][0] * acc[ai][bj][m][0], o1 = b1 + gv[bj][1] * acc[ai][bj][m][1];
;                     u32x4 w; w.x = cvt_pk_bf16(o0[0], o0[1]); w.y = cvt_pk_bf16(o0[2], o0[3]); w.z = cvt_pk_bf16(o1[0], o1[1]); w.w = cvt_pk_bf16(o1[2], o1[3]);
.LBB0_467:
	s_min_i32 s1, s40, 64
	s_lshr_b32 s1, s1, 5
	s_mul_i32 s22, s1, 0x1800
	s_ashr_i32 s23, s22, 31
	s_lshl_b32 s42, s40, 8
	s_lshl_b64 s[22:23], s[22:23], 2
	s_add_u32 s40, s62, s22
	s_addc_u32 s41, s63, s23
	s_lshl_b32 s1, s0, 8
	v_mov_b32_e32 v160, v229
	v_mov_b32_e32 v161, v228
	s_or_b32 s1, s1, s70
	s_add_u32 s22, s66, s22
	v_lshl_add_u32 v198, v161, 3, s1
	v_ashrrev_i32_e32 v199, 31, v198
	v_lshlrev_b64 v[56:57], 2, v[198:199]
	v_lshl_add_u64 v[152:153], s[40:41], 0, v[56:57]
	s_addc_u32 s23, s67, s23
	v_lshl_add_u64 v[154:155], s[6:7], 0, v[56:57]
	v_lshl_add_u64 v[156:157], s[22:23], 0, v[56:57]
	global_load_dwordx4 v[64:67], v[152:153], off offset:16
	global_load_dwordx4 v[68:71], v[152:153], off
	global_load_dwordx4 v[56:59], v[154:155], off offset:16
	global_load_dwordx4 v[60:63], v[154:155], off
	global_load_dwordx4 v[144:147], v[156:157], off offset:16
	global_load_dwordx4 v[148:151], v[156:157], off
	s_ashr_i32 s43, s42, 31
	s_lshl_b64 s[40:41], s[42:43], 11
	v_add_u32_e32 v200, s69, v160
	s_add_u32 s22, s31, s40
	s_addc_u32 s23, s61, s41
	v_ashrrev_i32_e32 v201, 31, v200
	v_add_u32_e32 v220, 16, v200
	v_lshl_add_u64 v[202:203], v[198:199], 1, s[22:23]
	v_ashrrev_i32_e32 v221, 31, v220
	v_add_u32_e32 v208, 32, v200
	v_ashrrev_i32_e32 v209, 31, v208
	v_add_u32_e32 v204, 48, v200
	v_ashrrev_i32_e32 v205, 31, v204
	v_lshlrev_b64 v[216:217], 10, v[200:201]
	v_cmp_eq_u32_e32 vcc, 0, v161
	v_lshl_add_u64 v[226:227], v[216:217], 0, v[198:199]
	s_add_u32 s44, s64, s40
	s_addc_u32 s45, s65, s41
	s_waitcnt vmcnt(0)
	v_pk_add_f32 v[150:151], v[150:151], 1.0 op_sel_hi:[1,0]
	v_pk_add_f32 v[148:149], v[148:149], 1.0 op_sel_hi:[1,0]
	v_pk_mul_f32 v[192:193], v[62:63], v[150:151]
	v_pk_mul_f32 v[196:197], v[60:61], v[148:149]
	v_pk_add_f32 v[60:61], v[146:147], 1.0 op_sel_hi:[1,0]
	v_pk_add_f32 v[62:63], v[144:145], 1.0 op_sel_hi:[1,0]
	v_pk_mul_f32 v[190:191], v[58:59], v[60:61]
	v_pk_mul_f32 v[194:195], v[56:57], v[62:63]
	global_load_dwordx4 v[56:59], v[152:153], off offset:528
	global_load_dwordx4 v[60:63], v[152:153], off offset:512
	global_load_dwordx4 v[144:147], v[154:155], off offset:528
	global_load_dwordx4 v[148:151], v[154:155], off offset:512
	s_nop 0
	global_load_dwordx4 v[152:155], v[156:157], off offset:528
	s_nop 0
	global_load_dwordx4 v[156:159], v[156:157], off offset:512
	s_waitcnt vmcnt(0)
	v_pk_add_f32 v[158:159], v[158:159], 1.0 op_sel_hi:[1,0]
	s_nop 0
	v_pk_mul_f32 v[188:189], v[150:151], v[158:159]
	v_pk_add_f32 v[150:151], v[152:153], 1.0 op_sel_hi:[1,0]
	v_pk_add_f32 v[156:157], v[156:157], 1.0 op_sel_hi:[1,0]
	v_pk_mul_f32 v[186:187], v[144:145], v[150:151]
	v_lshlrev_b64 v[144:145], 11, v[200:201]
	v_lshl_add_u64 v[224:225], v[202:203], 0, v[144:145]
	v_lshlrev_b64 v[144:145], 11, v[220:221]
	v_lshl_add_u64 v[222:223], v[202:203], 0, v[144:145]
	v_lshlrev_b64 v[144:145], 11, v[208:209]
	v_lshl_add_u64 v[210:211], v[202:203], 0, v[144:145]
	v_lshlrev_b64 v[144:145], 11, v[204:205]
	v_pk_mul_f32 v[182:183], v[148:149], v[156:157]
	v_pk_add_f32 v[148:149], v[154:155], 1.0 op_sel_hi:[1,0]
	v_lshl_add_u64 v[206:207], v[202:203], 0, v[144:145]
	v_pk_mul_f32 v[184:185], v[146:147], v[148:149]
	global_load_dwordx4 v[168:171], v[224:225], off offset:256
	global_load_dwordx4 v[164:167], v[222:223], off
	global_load_dwordx4 v[160:163], v[222:223], off offset:256
	global_load_dwordx4 v[156:159], v[210:211], off
	global_load_dwordx4 v[152:155], v[210:211], off offset:256
	global_load_dwordx4 v[148:151], v[206:207], off
	global_load_dwordx4 v[144:147], v[206:207], off offset:256
	global_load_dwordx4 v[216:219], v[224:225], off
	s_waitcnt vmcnt(0)
	v_lshlrev_b32_e32 v232, 16, v216
	v_and_b32_e32 v233, 0xffff0000, v216
	v_lshlrev_b32_e32 v216, 16, v217
	v_and_b32_e32 v217, 0xffff0000, v217
	v_lshlrev_b32_e32 v234, 16, v218
	v_and_b32_e32 v235, 0xffff0000, v218
	v_lshlrev_b32_e32 v218, 16, v219
	v_and_b32_e32 v219, 0xffff0000, v219
	v_pk_fma_f32 v[142:143], v[142:143], v[70:71], v[216:217]
	v_pk_fma_f32 v[140:141], v[140:141], v[68:69], v[232:233]
	v_pk_fma_f32 v[216:217], v[138:139], v[66:67], v[218:219]
	v_pk_fma_f32 v[218:219], v[136:137], v[64:65], v[234:235]
	v_cvt_pk_bf16_f32 v136, v140, v141
	v_cvt_pk_bf16_f32 v137, v142, v143
	s_nop 0
	v_cvt_pk_bf16_f32 v138, v218, v219
	v_cvt_pk_bf16_f32 v139, v216, v217
	global_store_dwordx4 v[224:225], v[136:139], off sc1
	s_nop 1
	v_mul_f32_e32 v136, v141, v141
	v_mul_f32_e32 v137, v143, v143
	v_fmac_f32_e32 v136, v140, v140
	v_fmac_f32_e32 v137, v142, v142
	v_add_f32_e32 v136, v136, v137
	v_mul_f32_e32 v137, v219, v219
	v_mul_f32_e32 v138, v217, v217
	v_fmac_f32_e32 v137, v218, v218
	v_fmac_f32_e32 v138, v216, v216
	v_add_f32_e32 v137, v137, v138
	v_add_f32_e32 v201, v136, v137
	v_pk_mul_f32 v[138:139], v[192:193], v[142:143]
	v_pk_mul_f32 v[136:137], v[196:197], v[140:141]
	v_pk_mul_f32 v[140:141], v[190:191], v[216:217]
	v_pk_mul_f32 v[142:143], v[194:195], v[218:219]
	v_cvt_pk_bf16_f32 v136, v136, v137
	v_cvt_pk_bf16_f32 v137, v138, v139
	s_nop 0
	v_cvt_pk_bf16_f32 v138, v142, v143
	v_cvt_pk_bf16_f32 v139, v140, v141
	v_lshl_add_u64 v[140:141], v[226:227], 1, s[44:45]
	global_store_dwordx4 v[140:141], v[136:139], off sc1
	v_lshlrev_b32_e32 v142, 16, v170
	v_and_b32_e32 v143, 0xffff0000, v170
	v_lshlrev_b32_e32 v136, 16, v168
	v_and_b32_e32 v137, 0xffff0000, v168
	v_lshlrev_b32_e32 v138, 16, v169
	v_and_b32_e32 v139, 0xffff0000, v169
	v_lshlrev_b32_e32 v168, 16, v171
	v_and_b32_e32 v169, 0xffff0000, v171
	v_pk_fma_f32 v[134:135], v[134:135], v[62:63], v[138:139]
	v_pk_fma_f32 v[132:133], v[132:133], v[60:61], v[136:137]
	v_pk_fma_f32 v[138:139], v[128:129], v[56:57], v[142:143]
; __device__ __forceinline__ unsigned cvt_pk_bf16(float lo, float hi) { unsigned r; asm volatile("v_cvt_pk_bf16_f32 %0, %1, %2" : "=v"(r) : "v"(lo), "v"(hi)); return r; }
;     __device__ __forceinline__ void operator()(const f32x4 (&acc)[2][2][4][2], const Unit& u, int wr, int wc, int fr, int fq) const {
;     ...
;             for (int m = 0; m < 4; ++m) { const int rl = wr * 64 + fr + ai * HALF + m * 16; const size_t off = (size_t)rl * DM + col0; float sq = 0.f;
;                 bf16_t* hrow = h16 + (size_t)rowt * DM + off;
; #pragma unroll
;                 for (int bj = 0; bj < 2; ++bj) { f32x4 b0, b1;
;                     if (bb) { b0 = *(const f32x4*)(bb + off + bj * HALF); b1 = *(const f32x4*)(bb + off + bj * HALF + 4); }
;                     else { const u32x4 r = raw[m][bj];
;                         b0 = (f32x4){__uint_as_float(r.x << 16), __uint_as_float(r.x & 0xffff0000u), __uint_as_float(r.y << 16), __uint_as_float(r.y & 0xffff0000u)};
;                         b1 = (f32x4){__uint_as_float(r.z << 16), __uint_as_float(r.z & 0xffff0000u), __uint_as_float(r.w << 16), __uint_as_float(r.w & 0xffff0000u)}; }
;                     const f32x4 o0 = b0 + gv[bj][0] * acc[ai][bj][m][0], o1 = b1 + gv[bj][1] * acc[ai][bj][m][1];
;                     u32x4 w; w.x = cvt_pk_bf16(o0[0], o0[1]); w.y = cvt_pk_bf16(o0[2], o0[3]); w.z = cvt_pk_bf16(o1[0], o1[1]); w.w = cvt_pk_bf16(o1[2], o1[3]);
;                     *(u32x4*)(hrow + bj * HALF) = w;
;                     sq += ((o0[0] * o0[0] + o0[1] * o0[1]) + (o0[2] * o0[2] + o0[3] * o0[3])) + ((o1[0] * o1[0] + o1[1] * o1[1]) + (o1[2] * o1[2] + o1[3] * o1[3]));
;                     if (hb) { const f32x4 y0 = o0 * wv[bj][0], y1 = o1 * wv[bj][1]; u32x4 z; z.x = cvt_pk_bf16(y0[0], y0[1]); z.y = cvt_pk_bf16(y0[2], y0[3]); z.z = cvt_pk_bf16(y1[0], y1[1]); z.w = cvt_pk_bf16(y1[2], y1[3]);
;                         *(u32x4*)(hb + (size_t)rowt * DM + off + bj * HALF) = z; } }
;                 if (ssq) { sq += __shfl_xor(sq, 16); sq += __shfl_xor(sq, 32); if (fq == 0) ssq[(size_t)(rowt + rl) * 16 + u.pn * 4 + wc] = sq; } }
	v_cvt_pk_bf16_f32 v128, v132, v133
	v_cvt_pk_bf16_f32 v129, v134, v135
	v_pk_fma_f32 v[136:137], v[130:131], v[58:59], v[168:169]
	v_cvt_pk_bf16_f32 v130, v138, v139
	s_nop 0
	v_cvt_pk_bf16_f32 v131, v136, v137
	global_store_dwordx4 v[224:225], v[128:131], off offset:256 sc1
	s_nop 1
	v_mul_f32_e32 v128, v133, v133
	v_mul_f32_e32 v129, v135, v135
	v_fmac_f32_e32 v128, v132, v132
	v_fmac_f32_e32 v129, v134, v134
	v_add_f32_e32 v128, v128, v129
	v_mul_f32_e32 v129, v139, v139
	v_mul_f32_e32 v130, v137, v137
	v_fmac_f32_e32 v129, v138, v138
	v_fmac_f32_e32 v130, v136, v136
	v_add_f32_e32 v129, v129, v130
	v_add_f32_e32 v128, v128, v129
	v_add_f32_e32 v142, v128, v201
	v_pk_mul_f32 v[128:129], v[182:183], v[132:133]
	v_pk_mul_f32 v[130:131], v[188:189], v[134:135]
	v_cvt_pk_bf16_f32 v128, v128, v129
	v_pk_mul_f32 v[132:133], v[184:185], v[136:137]
	v_cvt_pk_bf16_f32 v129, v130, v131
	v_pk_mul_f32 v[134:135], v[186:187], v[138:139]
	s_nop 0
	v_cvt_pk_bf16_f32 v130, v134, v135
	v_cvt_pk_bf16_f32 v131, v132, v133
	global_store_dwordx4 v[140:141], v[128:131], off offset:256 sc1
	s_nop 1
	v_and_b32_e32 v129, 64, v246
	v_xor_b32_e32 v128, 16, v246
	v_add_u32_e32 v129, 64, v129
	v_cmp_lt_i32_e64 s[40:41], v128, v129
	v_xor_b32_e32 v131, 32, v246
	s_nop 0
	v_cndmask_b32_e64 v128, v246, v128, s[40:41]
	v_lshlrev_b32_e32 v128, 2, v128
	ds_bpermute_b32 v130, v128, v142
	v_cmp_lt_i32_e64 s[40:41], v131, v129
	s_waitcnt lgkmcnt(0)
	v_add_f32_e32 v130, v142, v130
	v_cndmask_b32_e64 v129, v246, v131, s[40:41]
	v_lshlrev_b32_e32 v129, 2, v129
	ds_bpermute_b32 v131, v129, v130
	s_and_saveexec_b64 s[40:41], vcc
	s_cbranch_execz .LBB0_469
	s_waitcnt lgkmcnt(0)
	v_add_f32_e32 v132, v130, v131
	v_add_u32_e32 v130, s42, v200
	v_ashrrev_i32_e32 v131, 31, v130
	s_lshl_b32 s22, s0, 2
	v_lshlrev_b64 v[130:131], 6, v[130:131]
	s_ashr_i32 s23, s22, 31
	v_lshl_add_u64 v[130:131], s[12:13], 0, v[130:131]
	v_lshl_add_u64 v[130:131], s[22:23], 2, v[130:131]
	s_lshl_b32 s8, s68, 2
	v_lshl_add_u64 v[130:131], v[130:131], 0, s[8:9]
	global_store_dword v[130:131], v132, off sc1
.LBB0_469:
	s_or_b64 exec, exec, s[40:41]
	v_lshlrev_b32_e32 v132, 16, v164
	v_and_b32_e32 v133, 0xffff0000, v164
	v_lshlrev_b32_e32 v134, 16, v165
	v_and_b32_e32 v135, 0xffff0000, v165
	v_lshlrev_b32_e32 v136, 16, v166
	v_and_b32_e32 v137, 0xffff0000, v166
	v_lshlrev_b32_e32 v138, 16, v167
	v_and_b32_e32 v139, 0xffff0000, v167
	v_pk_fma_f32 v[126:127], v[126:127], v[70:71], v[134:135]
	v_pk_fma_f32 v[124:125], v[124:125], v[68:69], v[132:133]
	v_pk_fma_f32 v[134:135], v[120:121], v[64:65], v[136:137]
	v_cvt_pk_bf16_f32 v120, v124, v125
	v_cvt_pk_bf16_f32 v121, v126, v127
	v_pk_fma_f32 v[132:133], v[122:123], v[66:67], v[138:139]
	v_cvt_pk_bf16_f32 v122, v134, v135
	s_waitcnt lgkmcnt(0)
	v_lshlrev_b64 v[130:131], 10, v[220:221]
	v_cvt_pk_bf16_f32 v123, v132, v133
	global_store_dwordx4 v[222:223], v[120:123], off sc1
	v_lshl_add_u64 v[130:131], v[130:131], 0, v[198:199]
	s_nop 0
	v_mul_f32_e32 v120, v125, v125
	v_mul_f32_e32 v121, v127, v127
	v_fmac_f32_e32 v120, v124, v124
	v_fmac_f32_e32 v121, v126, v126
	v_add_f32_e32 v120, v120, v121
	v_mul_f32_e32 v121, v135, v135
	v_mul_f32_e32 v122, v133, v133
	v_fmac_f32_e32 v121, v134, v134
	v_fmac_f32_e32 v122, v132, v132
	v_add_f32_e32 v121, v121, v122
	v_add_f32_e32 v136, v120, v121
	v_pk_mul_f32 v[122:123], v[192:193], v[126:127]
	v_pk_mul_f32 v[120:121], v[196:197], v[124:125]
	v_pk_mul_f32 v[124:125], v[190:191], v[132:133]
	v_pk_mul_f32 v[126:127], v[194:195], v[134:135]
	v_cvt_pk_bf16_f32 v120, v120, v121
	v_cvt_pk_bf16_f32 v121, v122, v123
	s_nop 0
	v_cvt_pk_bf16_f32 v122, v126, v127
	v_cvt_pk_bf16_f32 v123, v124, v125
	v_lshl_add_u64 v[124:125], v[130:131], 1, s[44:45]
	global_store_dwordx4 v[124:125], v[120:123], off sc1
	v_lshlrev_b32_e32 v126, 16, v162
	v_and_b32_e32 v127, 0xffff0000, v162
	v_lshlrev_b32_e32 v120, 16, v160
	v_and_b32_e32 v121, 0xffff0000, v160
	v_lshlrev_b32_e32 v122, 16, v161
	v_and_b32_e32 v123, 0xffff0000, v161
	v_lshlrev_b32_e32 v130, 16, v163
	v_and_b32_e32 v131, 0xffff0000, v163
	v_pk_fma_f32 v[118:119], v[118:119], v[62:63], v[122:123]
	v_pk_fma_f32 v[116:117], v[116:117], v[60:61], v[120:121]
	v_pk_fma_f32 v[122:123], v[112:113], v[56:57], v[126:127]
	v_cvt_pk_bf16_f32 v112, v116, v117
	v_cvt_pk_bf16_f32 v113, v118, v119
	v_pk_fma_f32 v[120:121], v[114:115], v[58:59], v[130:131]
	v_cvt_pk_bf16_f32 v114, v122, v123
	s_nop 0
	v_cvt_pk_bf16_f32 v115, v120, v121
	global_store_dwordx4 v[222:223], v[112:115], off offset:256 sc1
	s_nop 1
	v_mul_f32_e32 v112, v117, v117
	v_mul_f32_e32 v113, v119, v119
	v_fmac_f32_e32 v112, v116, v116
	v_fmac_f32_e32 v113, v118, v118
	v_add_f32_e32 v112, v112, v113
	v_mul_f32_e32 v113, v123, v123
	v_mul_f32_e32 v114, v121, v121
	v_fmac_f32_e32 v113, v122, v122
	v_fmac_f32_e32 v114, v120, v120
	v_add_f32_e32 v113, v113, v114
	v_add_f32_e32 v112, v112, v113
	v_add_f32_e32 v115, v136, v112
	ds_bpermute_b32 v126, v128, v115
	v_pk_mul_f32 v[112:113], v[182:183], v[116:117]
	v_pk_mul_f32 v[116:117], v[186:187], v[122:123]
	v_cvt_pk_bf16_f32 v114, v112, v113
	v_pk_mul_f32 v[118:119], v[188:189], v[118:119]
	s_waitcnt lgkmcnt(0)
	v_add_f32_e32 v112, v115, v126
	ds_bpermute_b32 v113, v129, v112
	v_pk_mul_f32 v[120:121], v[184:185], v[120:121]
	v_cvt_pk_bf16_f32 v115, v118, v119
	v_cvt_pk_bf16_f32 v116, v116, v117
	s_nop 0
	v_cvt_pk_bf16_f32 v117, v120, v121
	global_store_dwordx4 v[124:125], v[114:117], off offset:256 sc1
	s_and_saveexec_b64 s[40:41], vcc
	s_cbranch_execz .LBB0_471
	s_waitcnt lgkmcnt(0)
	v_add_f32_e32 v114, v112, v113
	v_add_u32_e32 v112, s42, v220
	v_ashrrev_i32_e32 v113, 31, v112
	s_lshl_b32 s22, s0, 2
	v_lshlrev_b64 v[112:113], 6, v[112:113]
	s_ashr_i32 s23, s22, 31
	v_lshl_add_u64 v[112:113], s[12:13], 0, v[112:113]
	v_lshl_add_u64 v[112:113], s[22:23], 2, v[112:113]
	s_lshl_b32 s8, s68, 2
	v_lshl_add_u64 v[112:113], v[112:113], 0, s[8:9]
	global_store_dword v[112:113], v114, off sc1
; __device__ __forceinline__ unsigned cvt_pk_bf16(float lo, float hi) { unsigned r; asm volatile("v_cvt_pk_bf16_f32 %0, %1, %2" : "=v"(r) : "v"(lo), "v"(hi)); return r; }
;     __device__ __forceinline__ void operator()(const f32x4 (&acc)[2][2][4][2], const Unit& u, int wr, int wc, int fr, int fq) const {
;     ...
;             for (int m = 0; m < 4; ++m) { const int rl = wr * 64 + fr + ai * HALF + m * 16; const size_t off = (size_t)rl * DM + col0; float sq = 0.f;
;                 bf16_t* hrow = h16 + (size_t)rowt * DM + off;
; #pragma unroll
;                 for (int bj = 0; bj < 2; ++bj) { f32x4 b0, b1;
;                     if (bb) { b0 = *(const f32x4*)(bb + off + bj * HALF); b1 = *(const f32x4*)(bb + off + bj * HALF + 4); }
;                     else { const u32x4 r = raw[m][bj];
;                         b0 = (f32x4){__uint_as_float(r.x << 16), __uint_as_float(r.x & 0xffff0000u), __uint_as_float(r.y << 16), __uint_as_float(r.y & 0xffff0000u)};
;                         b1 = (f32x4){__uint_as_float(r.z << 16), __uint_as_float(r.z & 0xffff0000u), __uint_as_float(r.w << 16), __uint_as_float(r.w & 0xffff0000u)}; }
;                     const f32x4 o0 = b0 + gv[bj][0] * acc[ai][bj][m][0], o1 = b1 + gv[bj][1] * acc[ai][bj][m][1];
;                     u32x4 w; w.x = cvt_pk_bf16(o0[0], o0[1]); w.y = cvt_pk_bf16(o0[2], o0[3]); w.z = cvt_pk_bf16(o1[0], o1[1]); w.w = cvt_pk_bf16(o1[2], o1[3]);
;                     *(u32x4*)(hrow + bj * HALF) = w;
;                     sq += ((o0[0] * o0[0] + o0[1] * o0[1]) + (o0[2] * o0[2] + o0[3] * o0[3])) + ((o1[0] * o1[0] + o1[1] * o1[1]) + (o1[2] * o1[2] + o1[3] * o1[3]));
;                     if (hb) { const f32x4 y0 = o0 * wv[bj][0], y1 = o1 * wv[bj][1]; u32x4 z; z.x = cvt_pk_bf16(y0[0], y0[1]); z.y = cvt_pk_bf16(y0[2], y0[3]); z.z = cvt_pk_bf16(y1[0], y1[1]); z.w = cvt_pk_bf16(y1[2], y1[3]);
;                         *(u32x4*)(hb + (size_t)rowt * DM + off + bj * HALF) = z; } }
;                 if (ssq) { sq += __shfl_xor(sq, 16); sq += __shfl_xor(sq, 32); if (fq == 0) ssq[(size_t)(rowt + rl) * 16 + u.pn * 4 + wc] = sq; } }
.LBB0_471:
	s_or_b64 exec, exec, s[40:41]
	v_lshlrev_b32_e32 v114, 16, v156
	v_and_b32_e32 v115, 0xffff0000, v156
	v_lshlrev_b32_e32 v116, 16, v157
	v_and_b32_e32 v117, 0xffff0000, v157
	v_lshlrev_b32_e32 v118, 16, v158
	v_and_b32_e32 v119, 0xffff0000, v158
	v_lshlrev_b32_e32 v120, 16, v159
	v_and_b32_e32 v121, 0xffff0000, v159
	v_pk_fma_f32 v[110:111], v[110:111], v[70:71], v[116:117]
	v_pk_fma_f32 v[108:109], v[108:109], v[68:69], v[114:115]
	v_pk_fma_f32 v[116:117], v[104:105], v[64:65], v[118:119]
	v_cvt_pk_bf16_f32 v104, v108, v109
	v_cvt_pk_bf16_f32 v105, v110, v111
	v_pk_fma_f32 v[114:115], v[106:107], v[66:67], v[120:121]
	v_cvt_pk_bf16_f32 v106, v116, v117
	s_waitcnt lgkmcnt(0)
	v_lshlrev_b64 v[112:113], 10, v[208:209]
	v_cvt_pk_bf16_f32 v107, v114, v115
	global_store_dwordx4 v[210:211], v[104:107], off sc1
	v_lshl_add_u64 v[112:113], v[112:113], 0, v[198:199]
	s_nop 0
	v_mul_f32_e32 v104, v109, v109
	v_mul_f32_e32 v105, v111, v111
	v_fmac_f32_e32 v104, v108, v108
	v_fmac_f32_e32 v105, v110, v110
	v_add_f32_e32 v104, v104, v105
	v_mul_f32_e32 v105, v117, v117
	v_mul_f32_e32 v106, v115, v115
	v_fmac_f32_e32 v105, v116, v116
	v_fmac_f32_e32 v106, v114, v114
	v_add_f32_e32 v105, v105, v106
	v_add_f32_e32 v118, v104, v105
	v_pk_mul_f32 v[106:107], v[192:193], v[110:111]
	v_pk_mul_f32 v[104:105], v[196:197], v[108:109]
	v_pk_mul_f32 v[108:109], v[190:191], v[114:115]
	v_pk_mul_f32 v[110:111], v[194:195], v[116:117]
	v_cvt_pk_bf16_f32 v104, v104, v105
	v_cvt_pk_bf16_f32 v105, v106, v107
	s_nop 0
	v_cvt_pk_bf16_f32 v106, v110, v111
	v_cvt_pk_bf16_f32 v107, v108, v109
	v_lshl_add_u64 v[108:109], v[112:113], 1, s[44:45]
	global_store_dwordx4 v[108:109], v[104:107], off sc1
	v_lshlrev_b32_e32 v110, 16, v154
	v_and_b32_e32 v111, 0xffff0000, v154
	v_lshlrev_b32_e32 v104, 16, v152
	v_and_b32_e32 v105, 0xffff0000, v152
	v_lshlrev_b32_e32 v106, 16, v153
	v_and_b32_e32 v107, 0xffff0000, v153
	v_lshlrev_b32_e32 v112, 16, v155
	v_and_b32_e32 v113, 0xffff0000, v155
	v_pk_fma_f32 v[102:103], v[102:103], v[62:63], v[106:107]
	v_pk_fma_f32 v[100:101], v[100:101], v[60:61], v[104:105]
	v_pk_fma_f32 v[106:107], v[96:97], v[56:57], v[110:111]
	v_cvt_pk_bf16_f32 v96, v100, v101
	v_cvt_pk_bf16_f32 v97, v102, v103
	v_pk_fma_f32 v[104:105], v[98:99], v[58:59], v[112:113]
	v_cvt_pk_bf16_f32 v98, v106, v107
	s_nop 0
	v_cvt_pk_bf16_f32 v99, v104, v105
	global_store_dwordx4 v[210:211], v[96:99], off offset:256 sc1
	s_nop 1
	v_mul_f32_e32 v96, v101, v101
	v_mul_f32_e32 v97, v103, v103
	v_fmac_f32_e32 v96, v100, v100
	v_fmac_f32_e32 v97, v102, v102
	v_add_f32_e32 v96, v96, v97
	v_mul_f32_e32 v97, v107, v107
	v_mul_f32_e32 v98, v105, v105
	v_fmac_f32_e32 v97, v106, v106
	v_fmac_f32_e32 v98, v104, v104
	v_add_f32_e32 v97, v97, v98
	v_add_f32_e32 v96, v96, v97
	v_add_f32_e32 v99, v118, v96
	ds_bpermute_b32 v110, v128, v99
	v_pk_mul_f32 v[96:97], v[182:183], v[100:101]
	v_pk_mul_f32 v[100:101], v[186:187], v[106:107]
	v_cvt_pk_bf16_f32 v98, v96, v97
	v_pk_mul_f32 v[102:103], v[188:189], v[102:103]
	s_waitcnt lgkmcnt(0)
	v_add_f32_e32 v96, v99, v110
	ds_bpermute_b32 v97, v129, v96
	v_pk_mul_f32 v[104:105], v[184:185], v[104:105]
	v_cvt_pk_bf16_f32 v99, v102, v103
	v_cvt_pk_bf16_f32 v100, v100, v101
	s_nop 0
	v_cvt_pk_bf16_f32 v101, v104, v105
	global_store_dwordx4 v[108:109], v[98:101], off offset:256 sc1
	s_and_saveexec_b64 s[40:41], vcc
	s_cbranch_execz .LBB0_473
	s_waitcnt lgkmcnt(0)
	v_add_f32_e32 v98, v96, v97
	v_add_u32_e32 v96, s42, v208
	v_ashrrev_i32_e32 v97, 31, v96
	s_lshl_b32 s22, s0, 2
	v_lshlrev_b64 v[96:97], 6, v[96:97]
	s_ashr_i32 s23, s22, 31
	v_lshl_add_u64 v[96:97], s[12:13], 0, v[96:97]
	v_lshl_add_u64 v[96:97], s[22:23], 2, v[96:97]
	s_lshl_b32 s8, s68, 2
	v_lshl_add_u64 v[96:97], v[96:97], 0, s[8:9]
	global_store_dword v[96:97], v98, off sc1
.LBB0_473:
	s_or_b64 exec, exec, s[40:41]
	v_lshlrev_b32_e32 v98, 16, v148
	v_and_b32_e32 v99, 0xffff0000, v148
	v_lshlrev_b32_e32 v100, 16, v149
	v_and_b32_e32 v101, 0xffff0000, v149
	v_lshlrev_b32_e32 v102, 16, v150
	v_and_b32_e32 v103, 0xffff0000, v150
	v_lshlrev_b32_e32 v104, 16, v151
	v_and_b32_e32 v105, 0xffff0000, v151
	v_pk_fma_f32 v[94:95], v[94:95], v[70:71], v[100:101]
	v_pk_fma_f32 v[92:93], v[92:93], v[68:69], v[98:99]
	v_pk_fma_f32 v[100:101], v[88:89], v[64:65], v[102:103]
	v_cvt_pk_bf16_f32 v88, v92, v93
	v_cvt_pk_bf16_f32 v89, v94, v95
	v_pk_fma_f32 v[98:99], v[90:91], v[66:67], v[104:105]
	v_cvt_pk_bf16_f32 v90, v100, v101
	s_waitcnt lgkmcnt(0)
	v_lshlrev_b64 v[96:97], 10, v[204:205]
	v_cvt_pk_bf16_f32 v91, v98, v99
	global_store_dwordx4 v[206:207], v[88:91], off sc1
	v_lshl_add_u64 v[96:97], v[96:97], 0, v[198:199]
	s_nop 0
	v_mul_f32_e32 v88, v93, v93
	v_mul_f32_e32 v89, v95, v95
	v_fmac_f32_e32 v88, v92, v92
	v_fmac_f32_e32 v89, v94, v94
	v_add_f32_e32 v88, v88, v89
	v_mul_f32_e32 v89, v101, v101
	v_mul_f32_e32 v90, v99, v99
	v_fmac_f32_e32 v89, v100, v100
	v_fmac_f32_e32 v90, v98, v98
	v_add_f32_e32 v89, v89, v90
	v_add_f32_e32 v102, v88, v89
	v_pk_mul_f32 v[90:91], v[192:193], v[94:95]
	v_pk_mul_f32 v[88:89], v[196:197], v[92:93]
	v_pk_mul_f32 v[92:93], v[190:191], v[98:99]
	v_pk_mul_f32 v[94:95], v[194:195], v[100:101]
	v_cvt_pk_bf16_f32 v88, v88, v89
	v_cvt_pk_bf16_f32 v89, v90, v91
	s_nop 0
	v_cvt_pk_bf16_f32 v90, v94, v95
	v_cvt_pk_bf16_f32 v91, v92, v93
	v_lshl_add_u64 v[92:93], v[96:97], 1, s[44:45]
	global_store_dwordx4 v[92:93], v[88:91], off sc1
	v_lshlrev_b32_e32 v94, 16, v146
	v_and_b32_e32 v95, 0xffff0000, v146
	v_lshlrev_b32_e32 v88, 16, v144
	v_and_b32_e32 v89, 0xffff0000, v144
	v_lshlrev_b32_e32 v90, 16, v145
	v_and_b32_e32 v91, 0xffff0000, v145
	v_lshlrev_b32_e32 v96, 16, v147
	v_and_b32_e32 v97, 0xffff0000, v147
	v_pk_fma_f32 v[86:87], v[86:87], v[62:63], v[90:91]
	v_pk_fma_f32 v[84:85], v[84:85], v[60:61], v[88:89]
	v_pk_fma_f32 v[90:91], v[80:81], v[56:57], v[94:95]
	v_cvt_pk_bf16_f32 v80, v84, v85
	v_cvt_pk_bf16_f32 v81, v86, v87
	v_pk_fma_f32 v[88:89], v[82:83], v[58:59], v[96:97]
	v_cvt_pk_bf16_f32 v82, v90, v91
	s_nop 0
	v_cvt_pk_bf16_f32 v83, v88, v89
	global_store_dwordx4 v[206:207], v[80:83], off offset:256 sc1
	s_nop 1
	v_mul_f32_e32 v80, v85, v85
	v_mul_f32_e32 v81, v87, v87
	v_fmac_f32_e32 v80, v84, v84
	v_fmac_f32_e32 v81, v86, v86
	v_add_f32_e32 v80, v80, v81
	v_mul_f32_e32 v81, v91, v91
	v_mul_f32_e32 v82, v89, v89
	v_fmac_f32_e32 v81, v90, v90
	v_fmac_f32_e32 v82, v88, v88
	v_add_f32_e32 v81, v81, v82
	v_add_f32_e32 v80, v80, v81
	v_add_f32_e32 v83, v102, v80
	ds_bpermute_b32 v94, v128, v83
	v_pk_mul_f32 v[80:81], v[182:183], v[84:85]
	v_pk_mul_f32 v[84:85], v[186:187], v[90:91]
	v_cvt_pk_bf16_f32 v82, v80, v81
	v_pk_mul_f32 v[86:87], v[188:189], v[86:87]
	s_waitcnt lgkmcnt(0)
	v_add_f32_e32 v80, v83, v94
	ds_bpermute_b32 v81, v129, v80
	v_pk_mul_f32 v[88:89], v[184:185], v[88:89]
	v_cvt_pk_bf16_f32 v83, v86, v87
	v_cvt_pk_bf16_f32 v84, v84, v85
	s_nop 0
	v_cvt_pk_bf16_f32 v85, v88, v89
	global_store_dwordx4 v[92:93], v[82:85], off offset:256 sc1
	s_and_saveexec_b64 s[40:41], vcc
	s_cbranch_execz .LBB0_475
; __device__ __forceinline__ unsigned cvt_pk_bf16(float lo, float hi) { unsigned r; asm volatile("v_cvt_pk_bf16_f32 %0, %1, %2" : "=v"(r) : "v"(lo), "v"(hi)); return r; }
;     __device__ __forceinline__ void operator()(const f32x4 (&acc)[2][2][4][2], const Unit& u, int wr, int wc, int fr, int fq) const {
;     ...
;             for (int m = 0; m < 4; ++m) { const int rl = wr * 64 + fr + ai * HALF + m * 16; const size_t off = (size_t)rl * DM + col0; float sq = 0.f;
;                 bf16_t* hrow = h16 + (size_t)rowt * DM + off;
; #pragma unroll
;                 for (int bj = 0; bj < 2; ++bj) { f32x4 b0, b1;
;                     if (bb) { b0 = *(const f32x4*)(bb + off + bj * HALF); b1 = *(const f32x4*)(bb + off + bj * HALF + 4); }
;                     else { const u32x4 r = raw[m][bj];
;                         b0 = (f32x4){__uint_as_float(r.x << 16), __uint_as_float(r.x & 0xffff0000u), __uint_as_float(r.y << 16), __uint_as_float(r.y & 0xffff0000u)};
;                         b1 = (f32x4){__uint_as_float(r.z << 16), __uint_as_float(r.z & 0xffff0000u), __uint_as_float(r.w << 16), __uint_as_float(r.w & 0xffff0000u)}; }
;                     const f32x4 o0 = b0 + gv[bj][0] * acc[ai][bj][m][0], o1 = b1 + gv[bj][1] * acc[ai][bj][m][1];
;                     u32x4 w; w.x = cvt_pk_bf16(o0[0], o0[1]); w.y = cvt_pk_bf16(o0[2], o0[3]); w.z = cvt_pk_bf16(o1[0], o1[1]); w.w = cvt_pk_bf16(o1[2], o1[3]);
;                     *(u32x4*)(hrow + bj * HALF) = w;
;                     sq += ((o0[0] * o0[0] + o0[1] * o0[1]) + (o0[2] * o0[2] + o0[3] * o0[3])) + ((o1[0] * o1[0] + o1[1] * o1[1]) + (o1[2] * o1[2] + o1[3] * o1[3]));
;                     if (hb) { const f32x4 y0 = o0 * wv[bj][0], y1 = o1 * wv[bj][1]; u32x4 z; z.x = cvt_pk_bf16(y0[0], y0[1]); z.y = cvt_pk_bf16(y0[2], y0[3]); z.z = cvt_pk_bf16(y1[0], y1[1]); z.w = cvt_pk_bf16(y1[2], y1[3]);
;                         *(u32x4*)(hb + (size_t)rowt * DM + off + bj * HALF) = z; } }
;                 if (ssq) { sq += __shfl_xor(sq, 16); sq += __shfl_xor(sq, 32); if (fq == 0) ssq[(size_t)(rowt + rl) * 16 + u.pn * 4 + wc] = sq; } }
	s_waitcnt lgkmcnt(0)
	v_add_f32_e32 v82, v80, v81
	v_add_u32_e32 v80, s42, v204
	v_ashrrev_i32_e32 v81, 31, v80
	s_lshl_b32 s22, s0, 2
	v_lshlrev_b64 v[80:81], 6, v[80:81]
	s_ashr_i32 s23, s22, 31
	v_lshl_add_u64 v[80:81], s[12:13], 0, v[80:81]
	v_lshl_add_u64 v[80:81], s[22:23], 2, v[80:81]
	s_lshl_b32 s8, s68, 2
	v_lshl_add_u64 v[80:81], v[80:81], 0, s[8:9]
	global_store_dword v[80:81], v82, off sc1
.LBB0_475:
	s_or_b64 exec, exec, s[40:41]
	v_add_u32_e32 v120, 0x80, v200
	v_ashrrev_i32_e32 v121, 31, v120
	v_add_u32_e32 v116, 0x90, v200
	s_waitcnt lgkmcnt(0)
	v_lshlrev_b64 v[80:81], 11, v[120:121]
	v_ashrrev_i32_e32 v117, 31, v116
	v_add_u32_e32 v112, 0xa0, v200
	v_lshl_add_u64 v[122:123], v[202:203], 0, v[80:81]
	v_lshlrev_b64 v[80:81], 11, v[116:117]
	v_ashrrev_i32_e32 v113, 31, v112
	v_add_u32_e32 v108, 0xb0, v200
	v_lshl_add_u64 v[118:119], v[202:203], 0, v[80:81]
	v_lshlrev_b64 v[80:81], 11, v[112:113]
	v_ashrrev_i32_e32 v109, 31, v108
	v_lshl_add_u64 v[114:115], v[202:203], 0, v[80:81]
	v_lshlrev_b64 v[80:81], 11, v[108:109]
	v_lshl_add_u64 v[110:111], v[202:203], 0, v[80:81]
	global_load_dwordx4 v[104:107], v[122:123], off offset:256
	global_load_dwordx4 v[100:103], v[118:119], off
	global_load_dwordx4 v[96:99], v[118:119], off offset:256
	global_load_dwordx4 v[92:95], v[114:115], off
	global_load_dwordx4 v[88:91], v[114:115], off offset:256
	global_load_dwordx4 v[84:87], v[110:111], off
	global_load_dwordx4 v[80:83], v[110:111], off offset:256
	global_load_dwordx4 v[130:133], v[122:123], off
	v_lshlrev_b64 v[124:125], 10, v[120:121]
	v_lshl_add_u64 v[124:125], v[124:125], 0, v[198:199]
	s_waitcnt vmcnt(0)
	v_lshlrev_b32_e32 v126, 16, v130
	v_and_b32_e32 v127, 0xffff0000, v130
	v_lshlrev_b32_e32 v130, 16, v131
	v_and_b32_e32 v131, 0xffff0000, v131
	v_lshlrev_b32_e32 v134, 16, v132
	v_and_b32_e32 v135, 0xffff0000, v132
	v_lshlrev_b32_e32 v132, 16, v133
	v_and_b32_e32 v133, 0xffff0000, v133
	v_pk_fma_f32 v[130:131], v[78:79], v[70:71], v[130:131]
	v_pk_fma_f32 v[76:77], v[76:77], v[68:69], v[126:127]
	v_pk_fma_f32 v[126:127], v[74:75], v[66:67], v[132:133]
	v_pk_fma_f32 v[132:133], v[72:73], v[64:65], v[134:135]
	v_cvt_pk_bf16_f32 v72, v76, v77
	v_cvt_pk_bf16_f32 v73, v130, v131
	s_nop 0
	v_cvt_pk_bf16_f32 v74, v132, v133
	v_cvt_pk_bf16_f32 v75, v126, v127
	global_store_dwordx4 v[122:123], v[72:75], off sc1
	s_nop 1
	v_mul_f32_e32 v72, v77, v77
	v_mul_f32_e32 v73, v131, v131
	v_fmac_f32_e32 v72, v76, v76
	v_fmac_f32_e32 v73, v130, v130
	v_add_f32_e32 v72, v72, v73
	v_mul_f32_e32 v73, v133, v133
	v_mul_f32_e32 v74, v127, v127
	v_fmac_f32_e32 v73, v132, v132
	v_fmac_f32_e32 v74, v126, v126
	v_add_f32_e32 v73, v73, v74
	v_add_f32_e32 v78, v72, v73
	v_pk_mul_f32 v[74:75], v[192:193], v[130:131]
	v_pk_mul_f32 v[72:73], v[196:197], v[76:77]
	v_pk_mul_f32 v[76:77], v[190:191], v[126:127]
	v_pk_mul_f32 v[126:127], v[194:195], v[132:133]
	v_cvt_pk_bf16_f32 v72, v72, v73
	v_cvt_pk_bf16_f32 v73, v74, v75
	s_nop 0
	v_cvt_pk_bf16_f32 v74, v126, v127
	v_cvt_pk_bf16_f32 v75, v76, v77
	v_lshl_add_u64 v[76:77], v[124:125], 1, s[44:45]
	global_store_dwordx4 v[76:77], v[72:75], off sc1
	s_nop 1
	v_lshlrev_b32_e32 v72, 16, v104
	v_and_b32_e32 v73, 0xffff0000, v104
	v_lshlrev_b32_e32 v74, 16, v105
	v_and_b32_e32 v75, 0xffff0000, v105
	v_lshlrev_b32_e32 v104, 16, v106
	v_and_b32_e32 v105, 0xffff0000, v106
	v_lshlrev_b32_e32 v106, 16, v107
	v_and_b32_e32 v107, 0xffff0000, v107
	v_pk_fma_f32 v[54:55], v[54:55], v[62:63], v[74:75]
	v_pk_fma_f32 v[52:53], v[52:53], v[60:61], v[72:73]
	v_pk_fma_f32 v[74:75], v[48:49], v[56:57], v[104:105]
	v_cvt_pk_bf16_f32 v48, v52, v53
	v_cvt_pk_bf16_f32 v49, v54, v55
	v_pk_fma_f32 v[72:73], v[50:51], v[58:59], v[106:107]
	v_cvt_pk_bf16_f32 v50, v74, v75
	s_nop 0
	v_cvt_pk_bf16_f32 v51, v72, v73
	global_store_dwordx4 v[122:123], v[48:51], off offset:256 sc1
	s_nop 1
	v_mul_f32_e32 v48, v53, v53
	v_mul_f32_e32 v49, v55, v55
	v_fmac_f32_e32 v48, v52, v52
	v_fmac_f32_e32 v49, v54, v54
	v_add_f32_e32 v48, v48, v49
	v_mul_f32_e32 v49, v75, v75
	v_mul_f32_e32 v50, v73, v73
	v_fmac_f32_e32 v49, v74, v74
	v_fmac_f32_e32 v50, v72, v72
	v_add_f32_e32 v49, v49, v50
	v_add_f32_e32 v48, v48, v49
	v_add_f32_e32 v78, v48, v78
	v_pk_mul_f32 v[48:49], v[182:183], v[52:53]
	v_pk_mul_f32 v[50:51], v[188:189], v[54:55]
	v_cvt_pk_bf16_f32 v48, v48, v49
	v_pk_mul_f32 v[52:53], v[184:185], v[72:73]
	v_pk_mul_f32 v[54:55], v[186:187], v[74:75]
	v_cvt_pk_bf16_f32 v49, v50, v51
	s_nop 0
	v_cvt_pk_bf16_f32 v50, v54, v55
	v_cvt_pk_bf16_f32 v51, v52, v53
	global_store_dwordx4 v[76:77], v[48:51], off offset:256 sc1
	ds_bpermute_b32 v48, v128, v78
	s_waitcnt lgkmcnt(0)
	v_add_f32_e32 v48, v78, v48
	ds_bpermute_b32 v49, v129, v48
	s_and_saveexec_b64 s[40:41], vcc
	s_cbranch_execz .LBB0_477
	s_waitcnt lgkmcnt(0)
	v_add_f32_e32 v50, v48, v49
	v_add_u32_e32 v48, s42, v120
	v_ashrrev_i32_e32 v49, 31, v48
	s_lshl_b32 s22, s0, 2
	v_lshlrev_b64 v[48:49], 6, v[48:49]
	s_ashr_i32 s23, s22, 31
	v_lshl_add_u64 v[48:49], s[12:13], 0, v[48:49]
	v_lshl_add_u64 v[48:49], s[22:23], 2, v[48:49]
	s_lshl_b32 s8, s68, 2
	v_lshl_add_u64 v[48:49], v[48:49], 0, s[8:9]
	global_store_dword v[48:49], v50, off sc1
; __device__ __forceinline__ unsigned cvt_pk_bf16(float lo, float hi) { unsigned r; asm volatile("v_cvt_pk_bf16_f32 %0, %1, %2" : "=v"(r) : "v"(lo), "v"(hi)); return r; }
;     __device__ __forceinline__ void operator()(const f32x4 (&acc)[2][2][4][2], const Unit& u, int wr, int wc, int fr, int fq) const {
;     ...
;             for (int m = 0; m < 4; ++m) { const int rl = wr * 64 + fr + ai * HALF + m * 16; const size_t off = (size_t)rl * DM + col0; float sq = 0.f;
;                 bf16_t* hrow = h16 + (size_t)rowt * DM + off;
; #pragma unroll
;                 for (int bj = 0; bj < 2; ++bj) { f32x4 b0, b1;
;                     if (bb) { b0 = *(const f32x4*)(bb + off + bj * HALF); b1 = *(const f32x4*)(bb + off + bj * HALF + 4); }
;                     else { const u32x4 r = raw[m][bj];
;                         b0 = (f32x4){__uint_as_float(r.x << 16), __uint_as_float(r.x & 0xffff0000u), __uint_as_float(r.y << 16), __uint_as_float(r.y & 0xffff0000u)};
;                         b1 = (f32x4){__uint_as_float(r.z << 16), __uint_as_float(r.z & 0xffff0000u), __uint_as_float(r.w << 16), __uint_as_float(r.w & 0xffff0000u)}; }
;                     const f32x4 o0 = b0 + gv[bj][0] * acc[ai][bj][m][0], o1 = b1 + gv[bj][1] * acc[ai][bj][m][1];
;                     u32x4 w; w.x = cvt_pk_bf16(o0[0], o0[1]); w.y = cvt_pk_bf16(o0[2], o0[3]); w.z = cvt_pk_bf16(o1[0], o1[1]); w.w = cvt_pk_bf16(o1[2], o1[3]);
;                     *(u32x4*)(hrow + bj * HALF) = w;
;                     sq += ((o0[0] * o0[0] + o0[1] * o0[1]) + (o0[2] * o0[2] + o0[3] * o0[3])) + ((o1[0] * o1[0] + o1[1] * o1[1]) + (o1[2] * o1[2] + o1[3] * o1[3]));
;                     if (hb) { const f32x4 y0 = o0 * wv[bj][0], y1 = o1 * wv[bj][1]; u32x4 z; z.x = cvt_pk_bf16(y0[0], y0[1]); z.y = cvt_pk_bf16(y0[2], y0[3]); z.z = cvt_pk_bf16(y1[0], y1[1]); z.w = cvt_pk_bf16(y1[2], y1[3]);
;                         *(u32x4*)(hb + (size_t)rowt * DM + off + bj * HALF) = z; } }
;                 if (ssq) { sq += __shfl_xor(sq, 16); sq += __shfl_xor(sq, 32); if (fq == 0) ssq[(size_t)(rowt + rl) * 16 + u.pn * 4 + wc] = sq; } }
.LBB0_477:
	s_or_b64 exec, exec, s[40:41]
	v_lshlrev_b32_e32 v50, 16, v100
	v_and_b32_e32 v51, 0xffff0000, v100
	v_lshlrev_b32_e32 v52, 16, v101
	v_and_b32_e32 v53, 0xffff0000, v101
	v_lshlrev_b32_e32 v54, 16, v102
	v_and_b32_e32 v55, 0xffff0000, v102
	v_lshlrev_b32_e32 v72, 16, v103
	v_and_b32_e32 v73, 0xffff0000, v103
	v_pk_fma_f32 v[46:47], v[46:47], v[70:71], v[52:53]
	v_pk_fma_f32 v[44:45], v[44:45], v[68:69], v[50:51]
	v_pk_fma_f32 v[52:53], v[40:41], v[64:65], v[54:55]
	v_cvt_pk_bf16_f32 v40, v44, v45
	v_cvt_pk_bf16_f32 v41, v46, v47
	v_pk_fma_f32 v[50:51], v[42:43], v[66:67], v[72:73]
	v_cvt_pk_bf16_f32 v42, v52, v53
	s_waitcnt lgkmcnt(0)
	v_lshlrev_b64 v[48:49], 10, v[116:117]
	v_cvt_pk_bf16_f32 v43, v50, v51
	global_store_dwordx4 v[118:119], v[40:43], off sc1
	v_lshl_add_u64 v[48:49], v[48:49], 0, v[198:199]
	s_nop 0
	v_mul_f32_e32 v40, v45, v45
	v_mul_f32_e32 v41, v47, v47
	v_fmac_f32_e32 v40, v44, v44
	v_fmac_f32_e32 v41, v46, v46
	v_add_f32_e32 v40, v40, v41
	v_mul_f32_e32 v41, v53, v53
	v_mul_f32_e32 v42, v51, v51
	v_fmac_f32_e32 v41, v52, v52
	v_fmac_f32_e32 v42, v50, v50
	v_add_f32_e32 v41, v41, v42
	v_add_f32_e32 v54, v40, v41
	v_pk_mul_f32 v[42:43], v[192:193], v[46:47]
	v_pk_mul_f32 v[40:41], v[196:197], v[44:45]
	v_pk_mul_f32 v[44:45], v[190:191], v[50:51]
	v_pk_mul_f32 v[46:47], v[194:195], v[52:53]
	v_cvt_pk_bf16_f32 v40, v40, v41
	v_cvt_pk_bf16_f32 v41, v42, v43
	s_nop 0
	v_cvt_pk_bf16_f32 v42, v46, v47
	v_cvt_pk_bf16_f32 v43, v44, v45
	v_lshl_add_u64 v[44:45], v[48:49], 1, s[44:45]
	global_store_dwordx4 v[44:45], v[40:43], off sc1
	v_lshlrev_b32_e32 v46, 16, v98
	v_and_b32_e32 v47, 0xffff0000, v98
	v_lshlrev_b32_e32 v40, 16, v96
	v_and_b32_e32 v41, 0xffff0000, v96
	v_lshlrev_b32_e32 v42, 16, v97
	v_and_b32_e32 v43, 0xffff0000, v97
	v_lshlrev_b32_e32 v48, 16, v99
	v_and_b32_e32 v49, 0xffff0000, v99
	v_pk_fma_f32 v[38:39], v[38:39], v[62:63], v[42:43]
	v_pk_fma_f32 v[36:37], v[36:37], v[60:61], v[40:41]
	v_pk_fma_f32 v[42:43], v[32:33], v[56:57], v[46:47]
	v_cvt_pk_bf16_f32 v32, v36, v37
	v_cvt_pk_bf16_f32 v33, v38, v39
	v_pk_fma_f32 v[40:41], v[34:35], v[58:59], v[48:49]
	v_cvt_pk_bf16_f32 v34, v42, v43
	s_nop 0
	v_cvt_pk_bf16_f32 v35, v40, v41
	global_store_dwordx4 v[118:119], v[32:35], off offset:256 sc1
	s_nop 1
	v_mul_f32_e32 v32, v37, v37
	v_mul_f32_e32 v33, v39, v39
	v_fmac_f32_e32 v32, v36, v36
	v_fmac_f32_e32 v33, v38, v38
	v_add_f32_e32 v32, v32, v33
	v_mul_f32_e32 v33, v43, v43
	v_mul_f32_e32 v34, v41, v41
	v_fmac_f32_e32 v33, v42, v42
	v_fmac_f32_e32 v34, v40, v40
	v_add_f32_e32 v33, v33, v34
	v_add_f32_e32 v32, v32, v33
	v_add_f32_e32 v35, v54, v32
	ds_bpermute_b32 v46, v128, v35
	v_pk_mul_f32 v[32:33], v[182:183], v[36:37]
	v_pk_mul_f32 v[36:37], v[186:187], v[42:43]
	v_cvt_pk_bf16_f32 v34, v32, v33
	v_pk_mul_f32 v[38:39], v[188:189], v[38:39]
	s_waitcnt lgkmcnt(0)
	v_add_f32_e32 v32, v35, v46
	ds_bpermute_b32 v33, v129, v32
	v_pk_mul_f32 v[40:41], v[184:185], v[40:41]
	v_cvt_pk_bf16_f32 v35, v38, v39
	v_cvt_pk_bf16_f32 v36, v36, v37
	s_nop 0
	v_cvt_pk_bf16_f32 v37, v40, v41
	global_store_dwordx4 v[44:45], v[34:37], off offset:256 sc1
	s_and_saveexec_b64 s[40:41], vcc
	s_cbranch_execz .LBB0_479
	s_waitcnt lgkmcnt(0)
	v_add_f32_e32 v34, v32, v33
	v_add_u32_e32 v32, s42, v116
	v_ashrrev_i32_e32 v33, 31, v32
	s_lshl_b32 s22, s0, 2
	v_lshlrev_b64 v[32:33], 6, v[32:33]
	s_ashr_i32 s23, s22, 31
	v_lshl_add_u64 v[32:33], s[12:13], 0, v[32:33]
	v_lshl_add_u64 v[32:33], s[22:23], 2, v[32:33]
	s_lshl_b32 s8, s68, 2
	v_lshl_add_u64 v[32:33], v[32:33], 0, s[8:9]
	global_store_dword v[32:33], v34, off sc1
; __device__ __forceinline__ unsigned cvt_pk_bf16(float lo, float hi) { unsigned r; asm volatile("v_cvt_pk_bf16_f32 %0, %1, %2" : "=v"(r) : "v"(lo), "v"(hi)); return r; }
;     __device__ __forceinline__ void operator()(const f32x4 (&acc)[2][2][4][2], const Unit& u, int wr, int wc, int fr, int fq) const {
;     ...
;             for (int m = 0; m < 4; ++m) { const int rl = wr * 64 + fr + ai * HALF + m * 16; const size_t off = (size_t)rl * DM + col0; float sq = 0.f;
;                 bf16_t* hrow = h16 + (size_t)rowt * DM + off;
; #pragma unroll
;                 for (int bj = 0; bj < 2; ++bj) { f32x4 b0, b1;
;                     if (bb) { b0 = *(const f32x4*)(bb + off + bj * HALF); b1 = *(const f32x4*)(bb + off + bj * HALF + 4); }
;                     else { const u32x4 r = raw[m][bj];
;                         b0 = (f32x4){__uint_as_float(r.x << 16), __uint_as_float(r.x & 0xffff0000u), __uint_as_float(r.y << 16), __uint_as_float(r.y & 0xffff0000u)};
;                         b1 = (f32x4){__uint_as_float(r.z << 16), __uint_as_float(r.z & 0xffff0000u), __uint_as_float(r.w << 16), __uint_as_float(r.w & 0xffff0000u)}; }
;                     const f32x4 o0 = b0 + gv[bj][0] * acc[ai][bj][m][0], o1 = b1 + gv[bj][1] * acc[ai][bj][m][1];
;                     u32x4 w; w.x = cvt_pk_bf16(o0[0], o0[1]); w.y = cvt_pk_bf16(o0[2], o0[3]); w.z = cvt_pk_bf16(o1[0], o1[1]); w.w = cvt_pk_bf16(o1[2], o1[3]);
;                     *(u32x4*)(hrow + bj * HALF) = w;
;                     sq += ((o0[0] * o0[0] + o0[1] * o0[1]) + (o0[2] * o0[2] + o0[3] * o0[3])) + ((o1[0] * o1[0] + o1[1] * o1[1]) + (o1[2] * o1[2] + o1[3] * o1[3]));
;                     if (hb) { const f32x4 y0 = o0 * wv[bj][0], y1 = o1 * wv[bj][1]; u32x4 z; z.x = cvt_pk_bf16(y0[0], y0[1]); z.y = cvt_pk_bf16(y0[2], y0[3]); z.z = cvt_pk_bf16(y1[0], y1[1]); z.w = cvt_pk_bf16(y1[2], y1[3]);
;                         *(u32x4*)(hb + (size_t)rowt * DM + off + bj * HALF) = z; } }
;                 if (ssq) { sq += __shfl_xor(sq, 16); sq += __shfl_xor(sq, 32); if (fq == 0) ssq[(size_t)(rowt + rl) * 16 + u.pn * 4 + wc] = sq; } }
.LBB0_479:
	s_or_b64 exec, exec, s[40:41]
	v_lshlrev_b32_e32 v34, 16, v92
	v_and_b32_e32 v35, 0xffff0000, v92
	v_lshlrev_b32_e32 v36, 16, v93
	v_and_b32_e32 v37, 0xffff0000, v93
	v_lshlrev_b32_e32 v38, 16, v94
	v_and_b32_e32 v39, 0xffff0000, v94
	v_lshlrev_b32_e32 v40, 16, v95
	v_and_b32_e32 v41, 0xffff0000, v95
	v_pk_fma_f32 v[30:31], v[30:31], v[70:71], v[36:37]
	v_pk_fma_f32 v[28:29], v[28:29], v[68:69], v[34:35]
	v_pk_fma_f32 v[36:37], v[24:25], v[64:65], v[38:39]
	v_cvt_pk_bf16_f32 v24, v28, v29
	v_cvt_pk_bf16_f32 v25, v30, v31
	v_pk_fma_f32 v[34:35], v[26:27], v[66:67], v[40:41]
	v_cvt_pk_bf16_f32 v26, v36, v37
	s_waitcnt lgkmcnt(0)
	v_lshlrev_b64 v[32:33], 10, v[112:113]
	v_cvt_pk_bf16_f32 v27, v34, v35
	global_store_dwordx4 v[114:115], v[24:27], off sc1
	v_lshl_add_u64 v[32:33], v[32:33], 0, v[198:199]
	s_nop 0
	v_mul_f32_e32 v24, v29, v29
	v_mul_f32_e32 v25, v31, v31
	v_fmac_f32_e32 v24, v28, v28
	v_fmac_f32_e32 v25, v30, v30
	v_add_f32_e32 v24, v24, v25
	v_mul_f32_e32 v25, v37, v37
	v_mul_f32_e32 v26, v35, v35
	v_fmac_f32_e32 v25, v36, v36
	v_fmac_f32_e32 v26, v34, v34
	v_add_f32_e32 v25, v25, v26
	v_add_f32_e32 v38, v24, v25
	v_pk_mul_f32 v[26:27], v[192:193], v[30:31]
	v_pk_mul_f32 v[24:25], v[196:197], v[28:29]
	v_pk_mul_f32 v[28:29], v[190:191], v[34:35]
	v_pk_mul_f32 v[30:31], v[194:195], v[36:37]
	v_cvt_pk_bf16_f32 v24, v24, v25
	v_cvt_pk_bf16_f32 v25, v26, v27
	s_nop 0
	v_cvt_pk_bf16_f32 v26, v30, v31
	v_cvt_pk_bf16_f32 v27, v28, v29
	v_lshl_add_u64 v[28:29], v[32:33], 1, s[44:45]
	global_store_dwordx4 v[28:29], v[24:27], off sc1
	v_lshlrev_b32_e32 v30, 16, v90
	v_and_b32_e32 v31, 0xffff0000, v90
	v_lshlrev_b32_e32 v24, 16, v88
	v_and_b32_e32 v25, 0xffff0000, v88
	v_lshlrev_b32_e32 v26, 16, v89
	v_and_b32_e32 v27, 0xffff0000, v89
	v_lshlrev_b32_e32 v32, 16, v91
	v_and_b32_e32 v33, 0xffff0000, v91
	v_pk_fma_f32 v[22:23], v[22:23], v[62:63], v[26:27]
	v_pk_fma_f32 v[20:21], v[20:21], v[60:61], v[24:25]
	v_pk_fma_f32 v[26:27], v[16:17], v[56:57], v[30:31]
	v_cvt_pk_bf16_f32 v16, v20, v21
	v_cvt_pk_bf16_f32 v17, v22, v23
	v_pk_fma_f32 v[24:25], v[18:19], v[58:59], v[32:33]
	v_cvt_pk_bf16_f32 v18, v26, v27
	s_nop 0
	v_cvt_pk_bf16_f32 v19, v24, v25
	global_store_dwordx4 v[114:115], v[16:19], off offset:256 sc1
	s_nop 1
	v_mul_f32_e32 v16, v21, v21
	v_mul_f32_e32 v17, v23, v23
	v_fmac_f32_e32 v16, v20, v20
	v_fmac_f32_e32 v17, v22, v22
	v_add_f32_e32 v16, v16, v17
	v_mul_f32_e32 v17, v27, v27
	v_mul_f32_e32 v18, v25, v25
	v_fmac_f32_e32 v17, v26, v26
	v_fmac_f32_e32 v18, v24, v24
	v_add_f32_e32 v17, v17, v18
	v_add_f32_e32 v16, v16, v17
	v_add_f32_e32 v19, v38, v16
	ds_bpermute_b32 v30, v128, v19
	v_pk_mul_f32 v[16:17], v[182:183], v[20:21]
	v_pk_mul_f32 v[20:21], v[186:187], v[26:27]
	v_cvt_pk_bf16_f32 v18, v16, v17
	v_pk_mul_f32 v[22:23], v[188:189], v[22:23]
	s_waitcnt lgkmcnt(0)
	v_add_f32_e32 v16, v19, v30
	ds_bpermute_b32 v17, v129, v16
	v_pk_mul_f32 v[24:25], v[184:185], v[24:25]
	v_cvt_pk_bf16_f32 v19, v22, v23
	v_cvt_pk_bf16_f32 v20, v20, v21
	s_nop 0
	v_cvt_pk_bf16_f32 v21, v24, v25
	global_store_dwordx4 v[28:29], v[18:21], off offset:256 sc1
	s_and_saveexec_b64 s[40:41], vcc
	s_cbranch_execz .LBB0_481
	s_waitcnt lgkmcnt(0)
	v_add_f32_e32 v18, v16, v17
	v_add_u32_e32 v16, s42, v112
	v_ashrrev_i32_e32 v17, 31, v16
	s_lshl_b32 s22, s0, 2
	v_lshlrev_b64 v[16:17], 6, v[16:17]
	s_ashr_i32 s23, s22, 31
	v_lshl_add_u64 v[16:17], s[12:13], 0, v[16:17]
	v_lshl_add_u64 v[16:17], s[22:23], 2, v[16:17]
	s_lshl_b32 s8, s68, 2
	v_lshl_add_u64 v[16:17], v[16:17], 0, s[8:9]
	global_store_dword v[16:17], v18, off sc1
.LBB0_481:
	s_or_b64 exec, exec, s[40:41]
	v_lshlrev_b32_e32 v18, 16, v84
	v_and_b32_e32 v19, 0xffff0000, v84
	v_lshlrev_b32_e32 v20, 16, v85
	v_and_b32_e32 v21, 0xffff0000, v85
	v_lshlrev_b32_e32 v22, 16, v86
	v_and_b32_e32 v23, 0xffff0000, v86
	v_lshlrev_b32_e32 v24, 16, v87
	v_and_b32_e32 v25, 0xffff0000, v87
	v_pk_fma_f32 v[14:15], v[14:15], v[70:71], v[20:21]
	v_pk_fma_f32 v[12:13], v[12:13], v[68:69], v[18:19]
	v_pk_fma_f32 v[20:21], v[8:9], v[64:65], v[22:23]
	v_cvt_pk_bf16_f32 v8, v12, v13
	v_cvt_pk_bf16_f32 v9, v14, v15
	v_pk_fma_f32 v[18:19], v[10:11], v[66:67], v[24:25]
	v_cvt_pk_bf16_f32 v10, v20, v21
	s_waitcnt lgkmcnt(0)
	v_lshlrev_b64 v[16:17], 10, v[108:109]
	v_cvt_pk_bf16_f32 v11, v18, v19
	global_store_dwordx4 v[110:111], v[8:11], off sc1
	v_lshl_add_u64 v[16:17], v[16:17], 0, v[198:199]
	s_nop 0
	v_mul_f32_e32 v8, v13, v13
	v_mul_f32_e32 v9, v15, v15
	v_fmac_f32_e32 v8, v12, v12
	v_fmac_f32_e32 v9, v14, v14
	v_add_f32_e32 v8, v8, v9
	v_mul_f32_e32 v9, v21, v21
	v_mul_f32_e32 v10, v19, v19
	v_fmac_f32_e32 v9, v20, v20
	v_fmac_f32_e32 v10, v18, v18
	v_add_f32_e32 v9, v9, v10
	v_add_f32_e32 v22, v8, v9
	v_pk_mul_f32 v[10:11], v[192:193], v[14:15]
	v_pk_mul_f32 v[8:9], v[196:197], v[12:13]
	v_pk_mul_f32 v[12:13], v[190:191], v[18:19]
	v_pk_mul_f32 v[14:15], v[194:195], v[20:21]
	v_cvt_pk_bf16_f32 v8, v8, v9
	v_cvt_pk_bf16_f32 v9, v10, v11
	s_nop 0
	v_cvt_pk_bf16_f32 v10, v14, v15
	v_cvt_pk_bf16_f32 v11, v12, v13
	v_lshl_add_u64 v[12:13], v[16:17], 1, s[44:45]
	global_store_dwordx4 v[12:13], v[8:11], off sc1
	v_lshlrev_b32_e32 v14, 16, v82
	v_and_b32_e32 v15, 0xffff0000, v82
	v_lshlrev_b32_e32 v8, 16, v80
	v_and_b32_e32 v9, 0xffff0000, v80
	v_lshlrev_b32_e32 v10, 16, v81
	v_and_b32_e32 v11, 0xffff0000, v81
	v_lshlrev_b32_e32 v16, 16, v83
	v_and_b32_e32 v17, 0xffff0000, v83
	v_pk_fma_f32 v[6:7], v[6:7], v[62:63], v[10:11]
	v_pk_fma_f32 v[4:5], v[4:5], v[60:61], v[8:9]
	v_pk_fma_f32 v[10:11], v[0:1], v[56:57], v[14:15]
	v_cvt_pk_bf16_f32 v0, v4, v5
	v_cvt_pk_bf16_f32 v1, v6, v7
	v_pk_fma_f32 v[8:9], v[2:3], v[58:59], v[16:17]
	v_cvt_pk_bf16_f32 v2, v10, v11
	s_nop 0
	v_cvt_pk_bf16_f32 v3, v8, v9
	global_store_dwordx4 v[110:111], v[0:3], off offset:256 sc1
	s_nop 1
	v_mul_f32_e32 v0, v5, v5
	v_mul_f32_e32 v1, v7, v7
	v_fmac_f32_e32 v0, v4, v4
	v_fmac_f32_e32 v1, v6, v6
	v_add_f32_e32 v0, v0, v1
	v_mul_f32_e32 v1, v11, v11
	v_mul_f32_e32 v2, v9, v9
	v_fmac_f32_e32 v1, v10, v10
	v_fmac_f32_e32 v2, v8, v8
	v_add_f32_e32 v1, v1, v2
	v_add_f32_e32 v0, v0, v1
	v_add_f32_e32 v3, v22, v0
	ds_bpermute_b32 v14, v128, v3
	v_pk_mul_f32 v[0:1], v[182:183], v[4:5]
	v_pk_mul_f32 v[4:5], v[186:187], v[10:11]
	v_cvt_pk_bf16_f32 v2, v0, v1
	v_pk_mul_f32 v[6:7], v[188:189], v[6:7]
	s_waitcnt lgkmcnt(0)
	v_add_f32_e32 v0, v3, v14
	ds_bpermute_b32 v1, v129, v0
	v_pk_mul_f32 v[8:9], v[184:185], v[8:9]
	v_cvt_pk_bf16_f32 v3, v6, v7
	v_cvt_pk_bf16_f32 v4, v4, v5
	s_nop 0
	v_cvt_pk_bf16_f32 v5, v8, v9
	global_store_dwordx4 v[12:13], v[2:5], off offset:256 sc1
	s_and_saveexec_b64 s[40:41], vcc
	s_cbranch_execz .LBB0_483
	s_waitcnt lgkmcnt(0)
	v_add_f32_e32 v2, v0, v1
	v_add_u32_e32 v0, s42, v108
	v_ashrrev_i32_e32 v1, 31, v0
	s_lshl_b32 s0, s0, 2
	v_lshlrev_b64 v[0:1], 6, v[0:1]
	s_ashr_i32 s1, s0, 31
	v_lshl_add_u64 v[0:1], s[12:13], 0, v[0:1]
	v_lshl_add_u64 v[0:1], s[0:1], 2, v[0:1]
	s_lshl_b32 s8, s68, 2
	v_lshl_add_u64 v[0:1], v[0:1], 0, s[8:9]
	global_store_dword v[0:1], v2, off sc1

; __device__ __forceinline__ unsigned xb_ld(unsigned* p)              { return __hip_atomic_load(p, __ATOMIC_RELAXED, __HIP_MEMORY_SCOPE_AGENT); }
; __device__ __forceinline__ unsigned xb_add(unsigned* p, unsigned v) { return __hip_atomic_fetch_add(p, v, __ATOMIC_RELAXED, __HIP_MEMORY_SCOPE_AGENT); }
; #define XB_SPIN(cond, bar) do { unsigned _sp = 0; while (cond) { __builtin_amdgcn_s_sleep(1); \
;     if ((++_sp & 255u) == 0u) { if (xb_ld(&(bar)[XB_TMO])) break; if (_sp > XB_SPIN_CAP) { atomicAdd(&(bar)[XB_TMO], 1u); break; } } } } while (0)
; __device__ __forceinline__ void xcd_barrier(const XcdBarrier& b, int tid) {
;     asm volatile("s_waitcnt vmcnt(0)" ::: "memory");
;     __syncthreads();
;     if (tid == 0) {
;         unsigned* bar = b.bar;
;         __builtin_amdgcn_s_waitcnt(0);
;         unsigned nloc = b.st[0], nx = b.st[1];
;         if (nloc == 0u) { xcd_barrier_complete(bar, b.x, nloc, nx); b.st[0] = nloc; b.st[1] = nx; }
;         const unsigned old = xb_add(&bar[XB_XSUB(b.x)], 1u);
;         const unsigned gen = old / nloc;
;         if (old + 1u == (gen + 1u) * nloc) {
;             __builtin_amdgcn_fence(__ATOMIC_RELEASE, "agent");
;             asm volatile("s_waitcnt vmcnt(0)" ::: "memory");
;             const unsigned og = xb_add(&bar[XB_TOP], 1u);
;             const unsigned tg = og / nx;
;             if (og + 1u == (tg + 1u) * nx) xb_add(&bar[XB_TOPGEN], 1u);
;             else XB_SPIN(xb_ld(&bar[XB_TOPGEN]) == tg, bar);
;             __builtin_amdgcn_fence(__ATOMIC_ACQUIRE, "agent");
;             xb_add(&bar[XB_XGEN(b.x)], 1u);
;             asm volatile("s_waitcnt vmcnt(0)" ::: "memory");
;         } else {
;             XB_SPIN(xb_ld(&bar[XB_XGEN(b.x)]) == gen, bar);
;             __builtin_amdgcn_fence(__ATOMIC_ACQUIRE, "agent");
;             asm volatile("s_waitcnt vmcnt(0)" ::: "memory");
;         }
;     }
;     __syncthreads();
; }
.LBB0_487:
	v_readlane_b32 s0, v254, 2
	s_add_i32 s74, s0, 3
	s_cmp_ge_i32 s74, s81
	s_cbranch_scc1 .LBB0_553
	s_waitcnt vmcnt(0) lgkmcnt(0)
	s_barrier
	v_readlane_b32 s100, v255, 59
	s_add_i32 s100, s100, 1
	v_writelane_b32 v255, s100, 59
	v_cmp_eq_u32_e32 vcc, 0, v215
	s_and_saveexec_b64 s[0:1], vcc
	s_cbranch_execz .Lgs_w_2
	s_load_dwordx2 s[2:3], s[94:95], 0xb8
	v_readlane_b32 s101, v255, 12
	s_and_b32 s101, s101, 63
	s_lshl_b32 s101, s101, 6
	s_cmp_lt_u32 s101, 0x800
	s_movk_i32 s7, 0x1400
	s_cselect_b32 s7, 0xc00, s7
	s_add_i32 s101, s101, s7
	s_lshl_b32 s100, s100, 2
	v_mov_b32_e32 v0, s101
	v_mov_b32_e32 v1, 1
	s_waitcnt lgkmcnt(0)
	s_add_u32 s2, s2, 0xe0000
	s_addc_u32 s3, s3, 0
	global_atomic_add v0, v1, s[2:3]
	buffer_inv sc1
	s_mov_b32 s6, 0
.Lgs_p_2:
	global_load_dword v2, v0, s[2:3] sc1
	s_waitcnt vmcnt(0)
	v_cmp_le_u32_e32 vcc, s100, v2
	s_cbranch_vccnz .Lgs_i_2
	s_sleep 1
	s_add_i32 s6, s6, 1
	s_cmp_lt_u32 s6, 0x100000
	s_cbranch_scc1 .Lgs_p_2

; __device__ __forceinline__ unsigned xb_add(unsigned* p, unsigned v) { return __hip_atomic_fetch_add(p, v, __ATOMIC_RELAXED, __HIP_MEMORY_SCOPE_AGENT); }
; __device__ __forceinline__ void xcd_barrier(const XcdBarrier& b, int tid) {
;     asm volatile("s_waitcnt vmcnt(0)" ::: "memory");
;     __syncthreads();
;     if (tid == 0) {
;         unsigned* bar = b.bar;
;         __builtin_amdgcn_s_waitcnt(0);
;         unsigned nloc = b.st[0], nx = b.st[1];
;         if (nloc == 0u) { xcd_barrier_complete(bar, b.x, nloc, nx); b.st[0] = nloc; b.st[1] = nx; }
;         const unsigned old = xb_add(&bar[XB_XSUB(b.x)], 1u);
.Lgs_w_2:
	s_or_b64 exec, exec, s[0:1]
	s_barrier
	s_branch .LBB0_553
.Lgs_orig_2:
	v_readlane_b32 s0, v254, 3
	v_readlane_b32 s1, v254, 4
	s_andn2_b64 vcc, exec, s[0:1]
	s_cbranch_vccnz .LBB0_500
	s_waitcnt lgkmcnt(0)
	s_barrier
	s_mov_b64 s[0:1], exec
	v_readlane_b32 s2, v255, 6
	v_readlane_b32 s3, v255, 7
	s_and_b64 s[2:3], s[0:1], s[2:3]
	s_mov_b64 exec, s[2:3]
	s_cbranch_execz .LBB0_499
	v_readlane_b32 s2, v254, 0
	v_readlane_b32 s3, v254, 1
	buffer_wbl2 sc1
	s_waitcnt vmcnt(0)
	s_load_dwordx2 s[2:3], s[2:3], 0x58
	s_mov_b64 s[6:7], exec
	v_mbcnt_lo_u32_b32 v1, s6, 0
	v_mbcnt_hi_u32_b32 v1, s7, v1
	v_cmp_eq_u32_e32 vcc, 0, v1
	s_waitcnt lgkmcnt(0)
	global_load_dword v0, v213, s[2:3] offset:40
	s_and_saveexec_b64 s[12:13], vcc
	s_cbranch_execz .LBB0_492
	s_bcnt1_i32_b64 s4, s[6:7]
	v_mov_b32_e32 v2, s4
	global_atomic_add v2, v213, v2, s[2:3] offset:32 sc0

;     __device__ __forceinline__ void operator()(const f32x4 (&acc)[2][2][4][2], const Unit& u, int wr, int wc, int fr, int fq) const {
;     ...
;         const int rowt = u.pm * BM, b = rowt >= MLAT ? 2 : (rowt >> 13);
;         const float* gp = gate + b * 6144; const int col0 = u.pn * BM + wc * 32 + 8 * fq;
;         f32x4 gv[2][2], wv[2][2];
; #pragma unroll
;         for (int bj = 0; bj < 2; ++bj)
; #pragma unroll
;             for (int n = 0; n < 2; ++n) { gv[bj][n] = *(const f32x4*)(gp + col0 + bj * HALF + n * 4); if (cs) gv[bj][n] = gv[bj][n] * *(const f32x4*)(cs + col0 + bj * HALF + n * 4);
;                 if (hb) wv[bj][n] = *(const f32x4*)(wn_g + col0 + bj * HALF + n * 4) * (*(const f32x4*)(wn_sc + b * 6144 + col0 + bj * HALF + n * 4) + 1.0f); }
;         const float* bb = base_lat ? (rowt >= MLAT ? base_ctx + (size_t)(rowt - MLAT) * DM : base_lat + (size_t)rowt * DM) : nullptr;
; #pragma unroll
;         for (int ai = 0; ai < 2; ++ai) {
;             u32x4 raw[4][2];
; #pragma unroll
;             for (int m = 0; m < 4; ++m)
; #pragma unroll
;                 for (int bj = 0; bj < 2; ++bj) raw[m][bj] = *(const u32x4*)(h16 + (size_t)rowt * DM + (size_t)(wr * 64 + fr + ai * HALF + m * 16) * DM + col0 + bj * HALF);
; #pragma unroll
;             for (int m = 0; m < 4; ++m) { const int rl = wr * 64 + fr + ai * HALF + m * 16; const size_t off = (size_t)rl * DM + col0; float sq = 0.f;
;                 bf16_t* hrow = h16 + (size_t)rowt * DM + off;
; #pragma unroll
;                 for (int bj = 0; bj < 2; ++bj) { f32x4 b0, b1;
;                     if (bb) { b0 = *(const f32x4*)(bb + off + bj * HALF); b1 = *(const f32x4*)(bb + off + bj * HALF + 4); }
.LBB0_1134:
	s_min_i32 s1, s40, 64
	s_lshr_b32 s1, s1, 5
	s_mul_i32 s22, s1, 0x1800
	s_ashr_i32 s23, s22, 31
	s_lshl_b32 s42, s40, 8
	s_lshl_b64 s[22:23], s[22:23], 2
	s_add_u32 s40, s62, s22
	s_addc_u32 s41, s63, s23
	s_lshl_b32 s1, s0, 8
	v_mov_b32_e32 v160, v229
	v_mov_b32_e32 v161, v228
	s_or_b32 s1, s1, s70
	s_add_u32 s22, s66, s22
	v_lshl_add_u32 v198, v161, 3, s1
	v_ashrrev_i32_e32 v199, 31, v198
	v_lshlrev_b64 v[56:57], 2, v[198:199]
	v_lshl_add_u64 v[152:153], s[40:41], 0, v[56:57]
	s_addc_u32 s23, s67, s23
	v_lshl_add_u64 v[154:155], s[6:7], 0, v[56:57]
	v_lshl_add_u64 v[156:157], s[22:23], 0, v[56:57]
	global_load_dwordx4 v[64:67], v[152:153], off offset:16
	global_load_dwordx4 v[68:71], v[152:153], off
	global_load_dwordx4 v[56:59], v[154:155], off offset:16
	global_load_dwordx4 v[60:63], v[154:155], off
	global_load_dwordx4 v[144:147], v[156:157], off offset:16
	global_load_dwordx4 v[148:151], v[156:157], off
	s_ashr_i32 s43, s42, 31
	s_lshl_b64 s[40:41], s[42:43], 11
	v_add_u32_e32 v200, s69, v160
	s_add_u32 s22, s31, s40
	s_addc_u32 s23, s61, s41
	v_ashrrev_i32_e32 v201, 31, v200
	v_add_u32_e32 v220, 16, v200
	v_lshl_add_u64 v[202:203], v[198:199], 1, s[22:23]
	v_ashrrev_i32_e32 v221, 31, v220
	v_add_u32_e32 v208, 32, v200
	v_ashrrev_i32_e32 v209, 31, v208
	v_add_u32_e32 v204, 48, v200
	v_ashrrev_i32_e32 v205, 31, v204
	v_cmp_eq_u32_e32 vcc, 0, v161
	v_lshlrev_b64 v[216:217], 10, v[200:201]
	v_lshl_add_u64 v[226:227], v[216:217], 0, v[198:199]
	s_add_u32 s44, s64, s40
	s_addc_u32 s45, s65, s41
	s_waitcnt vmcnt(0)
	v_pk_add_f32 v[150:151], v[150:151], 1.0 op_sel_hi:[1,0]
	v_pk_add_f32 v[148:149], v[148:149], 1.0 op_sel_hi:[1,0]
	v_pk_mul_f32 v[192:193], v[62:63], v[150:151]
	v_pk_mul_f32 v[196:197], v[60:61], v[148:149]
	v_pk_add_f32 v[60:61], v[146:147], 1.0 op_sel_hi:[1,0]
	v_pk_add_f32 v[62:63], v[144:145], 1.0 op_sel_hi:[1,0]
	v_pk_mul_f32 v[190:191], v[58:59], v[60:61]
	v_pk_mul_f32 v[194:195], v[56:57], v[62:63]
	global_load_dwordx4 v[56:59], v[152:153], off offset:528
	global_load_dwordx4 v[60:63], v[152:153], off offset:512
	global_load_dwordx4 v[144:147], v[154:155], off offset:528
	global_load_dwordx4 v[148:151], v[154:155], off offset:512
	s_nop 0
	global_load_dwordx4 v[152:155], v[156:157], off offset:528
	s_nop 0
	global_load_dwordx4 v[156:159], v[156:157], off offset:512
	s_waitcnt vmcnt(0)
	v_pk_add_f32 v[158:159], v[158:159], 1.0 op_sel_hi:[1,0]
	s_nop 0
	v_pk_mul_f32 v[188:189], v[150:151], v[158:159]
	v_pk_add_f32 v[150:151], v[152:153], 1.0 op_sel_hi:[1,0]
	v_pk_add_f32 v[156:157], v[156:157], 1.0 op_sel_hi:[1,0]
	v_pk_mul_f32 v[186:187], v[144:145], v[150:151]
	v_lshlrev_b64 v[144:145], 11, v[200:201]
	v_lshl_add_u64 v[224:225], v[202:203], 0, v[144:145]
	v_lshlrev_b64 v[144:145], 11, v[220:221]
	v_lshl_add_u64 v[222:223], v[202:203], 0, v[144:145]
	v_lshlrev_b64 v[144:145], 11, v[208:209]
	v_lshl_add_u64 v[210:211], v[202:203], 0, v[144:145]
	v_lshlrev_b64 v[144:145], 11, v[204:205]
	v_pk_mul_f32 v[182:183], v[148:149], v[156:157]
	v_pk_add_f32 v[148:149], v[154:155], 1.0 op_sel_hi:[1,0]
	v_lshl_add_u64 v[206:207], v[202:203], 0, v[144:145]
	v_pk_mul_f32 v[184:185], v[146:147], v[148:149]
	global_load_dwordx4 v[168:171], v[224:225], off offset:256
	global_load_dwordx4 v[164:167], v[222:223], off
	global_load_dwordx4 v[160:163], v[222:223], off offset:256
	global_load_dwordx4 v[156:159], v[210:211], off
	global_load_dwordx4 v[152:155], v[210:211], off offset:256
	global_load_dwordx4 v[148:151], v[206:207], off
	global_load_dwordx4 v[144:147], v[206:207], off offset:256
	global_load_dwordx4 v[232:235], v[224:225], off
	s_waitcnt vmcnt(0)
; __device__ __forceinline__ unsigned cvt_pk_bf16(float lo, float hi) { unsigned r; asm volatile("v_cvt_pk_bf16_f32 %0, %1, %2" : "=v"(r) : "v"(lo), "v"(hi)); return r; }
;     __device__ __forceinline__ void operator()(const f32x4 (&acc)[2][2][4][2], const Unit& u, int wr, int wc, int fr, int fq) const {
;     ...
;             for (int m = 0; m < 4; ++m) { const int rl = wr * 64 + fr + ai * HALF + m * 16; const size_t off = (size_t)rl * DM + col0; float sq = 0.f;
;                 bf16_t* hrow = h16 + (size_t)rowt * DM + off;
; #pragma unroll
;                 for (int bj = 0; bj < 2; ++bj) { f32x4 b0, b1;
;                     if (bb) { b0 = *(const f32x4*)(bb + off + bj * HALF); b1 = *(const f32x4*)(bb + off + bj * HALF + 4); }
;                     else { const u32x4 r = raw[m][bj];
;                         b0 = (f32x4){__uint_as_float(r.x << 16), __uint_as_float(r.x & 0xffff0000u), __uint_as_float(r.y << 16), __uint_as_float(r.y & 0xffff0000u)};
;                         b1 = (f32x4){__uint_as_float(r.z << 16), __uint_as_float(r.z & 0xffff0000u), __uint_as_float(r.w << 16), __uint_as_float(r.w & 0xffff0000u)}; }
;                     const f32x4 o0 = b0 + gv[bj][0] * acc[ai][bj][m][0], o1 = b1 + gv[bj][1] * acc[ai][bj][m][1];
;                     u32x4 w; w.x = cvt_pk_bf16(o0[0], o0[1]); w.y = cvt_pk_bf16(o0[2], o0[3]); w.z = cvt_pk_bf16(o1[0], o1[1]); w.w = cvt_pk_bf16(o1[2], o1[3]);
;                     *(u32x4*)(hrow + bj * HALF) = w;
;                     sq += ((o0[0] * o0[0] + o0[1] * o0[1]) + (o0[2] * o0[2] + o0[3] * o0[3])) + ((o1[0] * o1[0] + o1[1] * o1[1]) + (o1[2] * o1[2] + o1[3] * o1[3]));
;                     if (hb) { const f32x4 y0 = o0 * wv[bj][0], y1 = o1 * wv[bj][1]; u32x4 z; z.x = cvt_pk_bf16(y0[0], y0[1]); z.y = cvt_pk_bf16(y0[2], y0[3]); z.z = cvt_pk_bf16(y1[0], y1[1]); z.w = cvt_pk_bf16(y1[2], y1[3]);
;                         *(u32x4*)(hb + (size_t)rowt * DM + off + bj * HALF) = z; } }
;                 if (ssq) { sq += __shfl_xor(sq, 16); sq += __shfl_xor(sq, 32); if (fq == 0) ssq[(size_t)(rowt + rl) * 16 + u.pn * 4 + wc] = sq; } }
	v_lshlrev_b32_e32 v216, 16, v232
	v_and_b32_e32 v217, 0xffff0000, v232
	v_lshlrev_b32_e32 v218, 16, v233
	v_and_b32_e32 v219, 0xffff0000, v233
	v_lshlrev_b32_e32 v232, 16, v234
	v_and_b32_e32 v233, 0xffff0000, v234
	v_lshlrev_b32_e32 v234, 16, v235
	v_and_b32_e32 v235, 0xffff0000, v235
	v_pk_fma_f32 v[142:143], v[142:143], v[70:71], v[218:219]
	v_pk_fma_f32 v[140:141], v[140:141], v[68:69], v[216:217]
	v_pk_fma_f32 v[218:219], v[136:137], v[64:65], v[232:233]
	v_cvt_pk_bf16_f32 v136, v140, v141
	v_cvt_pk_bf16_f32 v137, v142, v143
	v_pk_fma_f32 v[216:217], v[138:139], v[66:67], v[234:235]
	v_cvt_pk_bf16_f32 v138, v218, v219
	s_nop 0
	v_cvt_pk_bf16_f32 v139, v216, v217
	global_store_dwordx4 v[224:225], v[136:139], off sc1
	s_nop 1
	v_mul_f32_e32 v136, v141, v141
	v_mul_f32_e32 v137, v143, v143
	v_fmac_f32_e32 v136, v140, v140
	v_fmac_f32_e32 v137, v142, v142
	v_add_f32_e32 v136, v136, v137
	v_mul_f32_e32 v137, v219, v219
	v_mul_f32_e32 v138, v217, v217
	v_fmac_f32_e32 v137, v218, v218
	v_fmac_f32_e32 v138, v216, v216
	v_add_f32_e32 v137, v137, v138
	v_add_f32_e32 v201, v136, v137
	v_pk_mul_f32 v[138:139], v[192:193], v[142:143]
	v_pk_mul_f32 v[136:137], v[196:197], v[140:141]
	v_pk_mul_f32 v[140:141], v[190:191], v[216:217]
	v_pk_mul_f32 v[142:143], v[194:195], v[218:219]
	v_cvt_pk_bf16_f32 v136, v136, v137
	v_cvt_pk_bf16_f32 v137, v138, v139
	s_nop 0
	v_cvt_pk_bf16_f32 v138, v142, v143
	v_cvt_pk_bf16_f32 v139, v140, v141
	v_lshl_add_u64 v[140:141], v[226:227], 1, s[44:45]
	global_store_dwordx4 v[140:141], v[136:139], off sc1
	v_lshlrev_b32_e32 v142, 16, v170
	v_and_b32_e32 v143, 0xffff0000, v170
	v_lshlrev_b32_e32 v136, 16, v168
	v_and_b32_e32 v137, 0xffff0000, v168
	v_lshlrev_b32_e32 v138, 16, v169
	v_and_b32_e32 v139, 0xffff0000, v169
	v_lshlrev_b32_e32 v168, 16, v171
	v_and_b32_e32 v169, 0xffff0000, v171
	v_pk_fma_f32 v[134:135], v[134:135], v[62:63], v[138:139]
	v_pk_fma_f32 v[132:133], v[132:133], v[60:61], v[136:137]
	v_pk_fma_f32 v[138:139], v[128:129], v[56:57], v[142:143]
	v_cvt_pk_bf16_f32 v128, v132, v133
	v_cvt_pk_bf16_f32 v129, v134, v135
	v_pk_fma_f32 v[136:137], v[130:131], v[58:59], v[168:169]
	v_cvt_pk_bf16_f32 v130, v138, v139
	s_nop 0
	v_cvt_pk_bf16_f32 v131, v136, v137
	global_store_dwordx4 v[224:225], v[128:131], off offset:256 sc1
	s_nop 1
	v_mul_f32_e32 v128, v133, v133
	v_mul_f32_e32 v129, v135, v135
	v_fmac_f32_e32 v128, v132, v132
	v_fmac_f32_e32 v129, v134, v134
	v_add_f32_e32 v128, v128, v129
	v_mul_f32_e32 v129, v139, v139
	v_mul_f32_e32 v130, v137, v137
	v_fmac_f32_e32 v129, v138, v138
	v_fmac_f32_e32 v130, v136, v136
	v_add_f32_e32 v129, v129, v130
	v_add_f32_e32 v128, v128, v129
	v_add_f32_e32 v142, v128, v201
	v_pk_mul_f32 v[128:129], v[182:183], v[132:133]
	v_pk_mul_f32 v[130:131], v[188:189], v[134:135]
	v_cvt_pk_bf16_f32 v128, v128, v129
	v_pk_mul_f32 v[132:133], v[184:185], v[136:137]
	v_cvt_pk_bf16_f32 v129, v130, v131
	v_pk_mul_f32 v[134:135], v[186:187], v[138:139]
	s_nop 0
	v_cvt_pk_bf16_f32 v130, v134, v135
	v_cvt_pk_bf16_f32 v131, v132, v133
	global_store_dwordx4 v[140:141], v[128:131], off offset:256 sc1
	s_nop 1
	v_and_b32_e32 v129, 64, v246
	v_xor_b32_e32 v128, 16, v246
	v_add_u32_e32 v129, 64, v129
	v_cmp_lt_i32_e64 s[40:41], v128, v129
	v_xor_b32_e32 v131, 32, v246
	s_nop 0
	v_cndmask_b32_e64 v128, v246, v128, s[40:41]
	v_lshlrev_b32_e32 v128, 2, v128
	ds_bpermute_b32 v130, v128, v142
	v_cmp_lt_i32_e64 s[40:41], v131, v129
	s_waitcnt lgkmcnt(0)
	v_add_f32_e32 v130, v142, v130
	v_cndmask_b32_e64 v129, v246, v131, s[40:41]
	v_lshlrev_b32_e32 v129, 2, v129
	ds_bpermute_b32 v131, v129, v130
	s_and_saveexec_b64 s[40:41], vcc
	s_cbranch_execz .LBB0_1136
	s_waitcnt lgkmcnt(0)
	v_add_f32_e32 v132, v130, v131
	v_add_u32_e32 v130, s42, v200
	v_ashrrev_i32_e32 v131, 31, v130
	s_lshl_b32 s22, s0, 2
	v_lshlrev_b64 v[130:131], 6, v[130:131]
	s_ashr_i32 s23, s22, 31
	v_lshl_add_u64 v[130:131], s[12:13], 0, v[130:131]
	v_lshl_add_u64 v[130:131], s[22:23], 2, v[130:131]
	s_lshl_b32 s8, s68, 2
	v_lshl_add_u64 v[130:131], v[130:131], 0, s[8:9]
	global_store_dword v[130:131], v132, off sc1

; __device__ __forceinline__ unsigned cvt_pk_bf16(float lo, float hi) { unsigned r; asm volatile("v_cvt_pk_bf16_f32 %0, %1, %2" : "=v"(r) : "v"(lo), "v"(hi)); return r; }
;     __device__ __forceinline__ void operator()(const f32x4 (&acc)[2][2][4][2], const Unit& u, int wr, int wc, int fr, int fq) const {
;     ...
;             for (int m = 0; m < 4; ++m) { const int rl = wr * 64 + fr + ai * HALF + m * 16; const size_t off = (size_t)rl * DM + col0; float sq = 0.f;
;                 bf16_t* hrow = h16 + (size_t)rowt * DM + off;
; #pragma unroll
;                 for (int bj = 0; bj < 2; ++bj) { f32x4 b0, b1;
;                     if (bb) { b0 = *(const f32x4*)(bb + off + bj * HALF); b1 = *(const f32x4*)(bb + off + bj * HALF + 4); }
;                     else { const u32x4 r = raw[m][bj];
;                         b0 = (f32x4){__uint_as_float(r.x << 16), __uint_as_float(r.x & 0xffff0000u), __uint_as_float(r.y << 16), __uint_as_float(r.y & 0xffff0000u)};
;                         b1 = (f32x4){__uint_as_float(r.z << 16), __uint_as_float(r.z & 0xffff0000u), __uint_as_float(r.w << 16), __uint_as_float(r.w & 0xffff0000u)}; }
;                     const f32x4 o0 = b0 + gv[bj][0] * acc[ai][bj][m][0], o1 = b1 + gv[bj][1] * acc[ai][bj][m][1];
;                     u32x4 w; w.x = cvt_pk_bf16(o0[0], o0[1]); w.y = cvt_pk_bf16(o0[2], o0[3]); w.z = cvt_pk_bf16(o1[0], o1[1]); w.w = cvt_pk_bf16(o1[2], o1[3]);
;                     *(u32x4*)(hrow + bj * HALF) = w;
;                     sq += ((o0[0] * o0[0] + o0[1] * o0[1]) + (o0[2] * o0[2] + o0[3] * o0[3])) + ((o1[0] * o1[0] + o1[1] * o1[1]) + (o1[2] * o1[2] + o1[3] * o1[3]));
;                     if (hb) { const f32x4 y0 = o0 * wv[bj][0], y1 = o1 * wv[bj][1]; u32x4 z; z.x = cvt_pk_bf16(y0[0], y0[1]); z.y = cvt_pk_bf16(y0[2], y0[3]); z.z = cvt_pk_bf16(y1[0], y1[1]); z.w = cvt_pk_bf16(y1[2], y1[3]);
;                         *(u32x4*)(hb + (size_t)rowt * DM + off + bj * HALF) = z; } }
;                 if (ssq) { sq += __shfl_xor(sq, 16); sq += __shfl_xor(sq, 32); if (fq == 0) ssq[(size_t)(rowt + rl) * 16 + u.pn * 4 + wc] = sq; } }
.LBB0_1417:
	s_waitcnt vmcnt(0)
	v_pk_fma_f32 v[134:135], v[134:135], v[50:51], v[146:147]
	v_pk_fma_f32 v[132:133], v[132:133], v[48:49], v[144:145]
	v_pk_fma_f32 v[140:141], v[128:129], v[52:53], v[140:141]
	v_cvt_pk_bf16_f32 v128, v132, v133
	v_cvt_pk_bf16_f32 v129, v134, v135
	v_mul_f32_e32 v199, v199, v199
	v_mul_f32_e32 v191, v191, v191
	v_pk_fma_f32 v[142:143], v[130:131], v[54:55], v[142:143]
	v_cvt_pk_bf16_f32 v130, v140, v141
	v_fmac_f32_e32 v199, v198, v198
	v_cvt_pk_bf16_f32 v131, v142, v143
	global_store_dwordx4 v[238:239], v[128:131], off offset:256 sc1
	v_fmac_f32_e32 v191, v190, v190
	v_add_f32_e32 v190, v199, v191
	v_mul_f32_e32 v128, v133, v133
	v_mul_f32_e32 v129, v135, v135
	v_fmac_f32_e32 v128, v132, v132
	v_fmac_f32_e32 v129, v134, v134
	v_mul_f32_e32 v191, v205, v205
	v_mul_f32_e32 v197, v197, v197
	v_add_f32_e32 v128, v128, v129
	v_mul_f32_e32 v129, v141, v141
	v_mul_f32_e32 v130, v143, v143
	v_fmac_f32_e32 v191, v204, v204
	v_fmac_f32_e32 v197, v196, v196
	v_fmac_f32_e32 v129, v140, v140
	v_fmac_f32_e32 v130, v142, v142
	v_add_f32_e32 v191, v191, v197
	v_add_f32_e32 v129, v129, v130
	v_add_f32_e32 v190, v190, v191
	v_add_f32_e32 v128, v128, v129
	v_and_b32_e32 v129, 64, v246
	v_add_f32_e32 v131, v190, v128
	v_xor_b32_e32 v128, 16, v246
	v_add_u32_e32 v144, 64, v129
	v_cmp_lt_i32_e32 vcc, v128, v144
	v_pk_add_f32 v[172:173], v[172:173], 1.0 op_sel_hi:[1,0]
	v_pk_add_f32 v[180:181], v[180:181], 1.0 op_sel_hi:[1,0]
	v_cndmask_b32_e32 v128, v246, v128, vcc
	v_pk_mul_f32 v[168:169], v[168:169], v[172:173]
	v_lshlrev_b32_e32 v172, 2, v128
	ds_bpermute_b32 v145, v172, v131
	v_pk_mul_f32 v[128:129], v[168:169], v[132:133]
	v_pk_add_f32 v[182:183], v[182:183], 1.0 op_sel_hi:[1,0]
	v_cvt_pk_bf16_f32 v130, v128, v129
	v_xor_b32_e32 v129, 32, v246
	v_cmp_lt_i32_e32 vcc, v129, v144
	s_waitcnt lgkmcnt(0)
	v_add_f32_e32 v128, v131, v145
	v_pk_mul_f32 v[176:177], v[176:177], v[180:181]
	v_cndmask_b32_e32 v129, v246, v129, vcc
	v_lshlrev_b32_e32 v173, 2, v129
	ds_bpermute_b32 v129, v173, v128
	v_pk_add_f32 v[174:175], v[174:175], 1.0 op_sel_hi:[1,0]
	v_cmp_eq_u32_e64 s[42:43], 0, v253
	v_pk_mul_f32 v[178:179], v[178:179], v[182:183]
	v_pk_mul_f32 v[170:171], v[170:171], v[174:175]
	v_pk_mul_f32 v[132:133], v[176:177], v[140:141]
	v_pk_mul_f32 v[134:135], v[170:171], v[134:135]
	v_pk_mul_f32 v[142:143], v[178:179], v[142:143]
	v_cvt_pk_bf16_f32 v131, v134, v135
	v_cvt_pk_bf16_f32 v132, v132, v133
	s_nop 0
	v_cvt_pk_bf16_f32 v133, v142, v143
	global_store_dwordx4 v[188:189], v[130:133], off offset:256 sc1
	s_and_saveexec_b64 s[76:77], s[42:43]
	s_cbranch_execz .LBB0_1419
	s_waitcnt lgkmcnt(0)
	v_add_f32_e32 v130, v128, v129
	v_add_u32_e32 v128, s70, v230
	v_ashrrev_i32_e32 v129, 31, v128
	s_lshl_b32 s52, s18, 2
	v_lshlrev_b64 v[128:129], 6, v[128:129]
	s_ashr_i32 s53, s52, 31
	v_lshl_add_u64 v[128:129], s[46:47], 0, v[128:129]
	v_lshl_add_u64 v[128:129], s[52:53], 2, v[128:129]
	s_lshl_b32 s8, s38, 2
	v_lshl_add_u64 v[128:129], v[128:129], 0, s[8:9]
	global_store_dword v[128:129], v130, off sc1

; __device__ __forceinline__ unsigned cvt_pk_bf16(float lo, float hi) { unsigned r; asm volatile("v_cvt_pk_bf16_f32 %0, %1, %2" : "=v"(r) : "v"(lo), "v"(hi)); return r; }
;     __device__ __forceinline__ void operator()(const f32x4 (&acc)[2][2][4][2], const Unit& u, int wr, int wc, int fr, int fq) const {
;     ...
;             for (int m = 0; m < 4; ++m) { const int rl = wr * 64 + fr + ai * HALF + m * 16; const size_t off = (size_t)rl * DM + col0; float sq = 0.f;
;                 bf16_t* hrow = h16 + (size_t)rowt * DM + off;
; #pragma unroll
;                 for (int bj = 0; bj < 2; ++bj) { f32x4 b0, b1;
;                     if (bb) { b0 = *(const f32x4*)(bb + off + bj * HALF); b1 = *(const f32x4*)(bb + off + bj * HALF + 4); }
;                     else { const u32x4 r = raw[m][bj];
;                         b0 = (f32x4){__uint_as_float(r.x << 16), __uint_as_float(r.x & 0xffff0000u), __uint_as_float(r.y << 16), __uint_as_float(r.y & 0xffff0000u)};
;                         b1 = (f32x4){__uint_as_float(r.z << 16), __uint_as_float(r.z & 0xffff0000u), __uint_as_float(r.w << 16), __uint_as_float(r.w & 0xffff0000u)}; }
;                     const f32x4 o0 = b0 + gv[bj][0] * acc[ai][bj][m][0], o1 = b1 + gv[bj][1] * acc[ai][bj][m][1];
;                     u32x4 w; w.x = cvt_pk_bf16(o0[0], o0[1]); w.y = cvt_pk_bf16(o0[2], o0[3]); w.z = cvt_pk_bf16(o1[0], o1[1]); w.w = cvt_pk_bf16(o1[2], o1[3]);
;                     *(u32x4*)(hrow + bj * HALF) = w;
;                     sq += ((o0[0] * o0[0] + o0[1] * o0[1]) + (o0[2] * o0[2] + o0[3] * o0[3])) + ((o1[0] * o1[0] + o1[1] * o1[1]) + (o1[2] * o1[2] + o1[3] * o1[3]));
;                     if (hb) { const f32x4 y0 = o0 * wv[bj][0], y1 = o1 * wv[bj][1]; u32x4 z; z.x = cvt_pk_bf16(y0[0], y0[1]); z.y = cvt_pk_bf16(y0[2], y0[3]); z.z = cvt_pk_bf16(y1[0], y1[1]); z.w = cvt_pk_bf16(y1[2], y1[3]);
;                         *(u32x4*)(hb + (size_t)rowt * DM + off + bj * HALF) = z; } }
;                 if (ssq) { sq += __shfl_xor(sq, 16); sq += __shfl_xor(sq, 32); if (fq == 0) ssq[(size_t)(rowt + rl) * 16 + u.pn * 4 + wc] = sq; } }
.LBB0_1425:
	v_mul_f32_e32 v133, v133, v133
	s_waitcnt vmcnt(0)
	v_pk_fma_f32 v[118:119], v[118:119], v[50:51], v[126:127]
	v_pk_fma_f32 v[116:117], v[116:117], v[48:49], v[124:125]
	v_pk_fma_f32 v[120:121], v[112:113], v[52:53], v[120:121]
	v_cvt_pk_bf16_f32 v112, v116, v117
	v_cvt_pk_bf16_f32 v113, v118, v119
	v_fmac_f32_e32 v133, v132, v132
	v_mul_f32_e32 v132, v135, v135
	v_pk_fma_f32 v[122:123], v[114:115], v[54:55], v[122:123]
	v_cvt_pk_bf16_f32 v114, v120, v121
	v_fmac_f32_e32 v132, v134, v134
	v_cvt_pk_bf16_f32 v115, v122, v123
	global_store_dwordx4 v[140:141], v[112:115], off offset:256 sc1
	v_add_f32_e32 v132, v133, v132
	v_mul_f32_e32 v133, v147, v147
	v_mul_f32_e32 v112, v117, v117
	v_mul_f32_e32 v113, v119, v119
	v_fmac_f32_e32 v112, v116, v116
	v_fmac_f32_e32 v113, v118, v118
	v_mul_f32_e32 v131, v131, v131
	v_add_f32_e32 v112, v112, v113
	v_mul_f32_e32 v113, v121, v121
	v_mul_f32_e32 v114, v123, v123
	v_fmac_f32_e32 v133, v146, v146
	v_fmac_f32_e32 v131, v130, v130
	v_fmac_f32_e32 v113, v120, v120
	v_fmac_f32_e32 v114, v122, v122
	v_add_f32_e32 v130, v133, v131
	v_add_f32_e32 v113, v113, v114
	v_add_f32_e32 v130, v132, v130
	v_add_f32_e32 v112, v112, v113
	v_add_f32_e32 v115, v130, v112
	ds_bpermute_b32 v124, v172, v115
	v_pk_mul_f32 v[112:113], v[168:169], v[116:117]
	v_pk_mul_f32 v[116:117], v[176:177], v[120:121]
	v_cvt_pk_bf16_f32 v114, v112, v113
	v_pk_mul_f32 v[118:119], v[170:171], v[118:119]
	s_waitcnt lgkmcnt(0)
	v_add_f32_e32 v112, v115, v124
	ds_bpermute_b32 v113, v173, v112
	v_pk_mul_f32 v[122:123], v[178:179], v[122:123]
	v_cvt_pk_bf16_f32 v115, v118, v119
	v_cvt_pk_bf16_f32 v116, v116, v117
	s_nop 0
	v_cvt_pk_bf16_f32 v117, v122, v123
	global_store_dwordx4 v[128:129], v[114:117], off offset:256 sc1
	s_and_saveexec_b64 s[76:77], s[42:43]
	s_cbranch_execz .LBB0_1427
	s_waitcnt lgkmcnt(0)
	v_add_f32_e32 v114, v112, v113
	v_add_u32_e32 v112, s70, v236
	v_ashrrev_i32_e32 v113, 31, v112
	s_lshl_b32 s52, s18, 2
	v_lshlrev_b64 v[112:113], 6, v[112:113]
	s_ashr_i32 s53, s52, 31
	v_lshl_add_u64 v[112:113], s[46:47], 0, v[112:113]
	v_lshl_add_u64 v[112:113], s[52:53], 2, v[112:113]
	s_lshl_b32 s8, s38, 2
	v_lshl_add_u64 v[112:113], v[112:113], 0, s[8:9]
	global_store_dword v[112:113], v114, off sc1

; __device__ __forceinline__ unsigned cvt_pk_bf16(float lo, float hi) { unsigned r; asm volatile("v_cvt_pk_bf16_f32 %0, %1, %2" : "=v"(r) : "v"(lo), "v"(hi)); return r; }
;     __device__ __forceinline__ void operator()(const f32x4 (&acc)[2][2][4][2], const Unit& u, int wr, int wc, int fr, int fq) const {
;     ...
;             for (int m = 0; m < 4; ++m) { const int rl = wr * 64 + fr + ai * HALF + m * 16; const size_t off = (size_t)rl * DM + col0; float sq = 0.f;
;                 bf16_t* hrow = h16 + (size_t)rowt * DM + off;
; #pragma unroll
;                 for (int bj = 0; bj < 2; ++bj) { f32x4 b0, b1;
;                     if (bb) { b0 = *(const f32x4*)(bb + off + bj * HALF); b1 = *(const f32x4*)(bb + off + bj * HALF + 4); }
;                     else { const u32x4 r = raw[m][bj];
;                         b0 = (f32x4){__uint_as_float(r.x << 16), __uint_as_float(r.x & 0xffff0000u), __uint_as_float(r.y << 16), __uint_as_float(r.y & 0xffff0000u)};
;                         b1 = (f32x4){__uint_as_float(r.z << 16), __uint_as_float(r.z & 0xffff0000u), __uint_as_float(r.w << 16), __uint_as_float(r.w & 0xffff0000u)}; }
;                     const f32x4 o0 = b0 + gv[bj][0] * acc[ai][bj][m][0], o1 = b1 + gv[bj][1] * acc[ai][bj][m][1];
;                     u32x4 w; w.x = cvt_pk_bf16(o0[0], o0[1]); w.y = cvt_pk_bf16(o0[2], o0[3]); w.z = cvt_pk_bf16(o1[0], o1[1]); w.w = cvt_pk_bf16(o1[2], o1[3]);
;                     *(u32x4*)(hrow + bj * HALF) = w;
;                     sq += ((o0[0] * o0[0] + o0[1] * o0[1]) + (o0[2] * o0[2] + o0[3] * o0[3])) + ((o1[0] * o1[0] + o1[1] * o1[1]) + (o1[2] * o1[2] + o1[3] * o1[3]));
;                     if (hb) { const f32x4 y0 = o0 * wv[bj][0], y1 = o1 * wv[bj][1]; u32x4 z; z.x = cvt_pk_bf16(y0[0], y0[1]); z.y = cvt_pk_bf16(y0[2], y0[3]); z.z = cvt_pk_bf16(y1[0], y1[1]); z.w = cvt_pk_bf16(y1[2], y1[3]);
;                         *(u32x4*)(hb + (size_t)rowt * DM + off + bj * HALF) = z; } }
;                 if (ssq) { sq += __shfl_xor(sq, 16); sq += __shfl_xor(sq, 32); if (fq == 0) ssq[(size_t)(rowt + rl) * 16 + u.pn * 4 + wc] = sq; } }
.LBB0_1433:
	v_mul_f32_e32 v117, v117, v117
	s_waitcnt vmcnt(0)
	v_pk_fma_f32 v[102:103], v[102:103], v[50:51], v[110:111]
	v_pk_fma_f32 v[100:101], v[100:101], v[48:49], v[108:109]
	v_pk_fma_f32 v[104:105], v[96:97], v[52:53], v[104:105]
	v_cvt_pk_bf16_f32 v96, v100, v101
	v_cvt_pk_bf16_f32 v97, v102, v103
	v_fmac_f32_e32 v117, v116, v116
	v_mul_f32_e32 v116, v119, v119
	v_pk_fma_f32 v[106:107], v[98:99], v[54:55], v[106:107]
	v_cvt_pk_bf16_f32 v98, v104, v105
	v_fmac_f32_e32 v116, v118, v118
	v_cvt_pk_bf16_f32 v99, v106, v107
	global_store_dwordx4 v[120:121], v[96:99], off offset:256 sc1
	v_add_f32_e32 v116, v117, v116
	v_mul_f32_e32 v117, v127, v127
	v_mul_f32_e32 v96, v101, v101
	v_mul_f32_e32 v97, v103, v103
	v_fmac_f32_e32 v96, v100, v100
	v_fmac_f32_e32 v97, v102, v102
	v_mul_f32_e32 v115, v115, v115
	v_add_f32_e32 v96, v96, v97
	v_mul_f32_e32 v97, v105, v105
	v_mul_f32_e32 v98, v107, v107
	v_fmac_f32_e32 v117, v126, v126
	v_fmac_f32_e32 v115, v114, v114
	v_fmac_f32_e32 v97, v104, v104
	v_fmac_f32_e32 v98, v106, v106
	v_add_f32_e32 v114, v117, v115
	v_add_f32_e32 v97, v97, v98
	v_add_f32_e32 v114, v116, v114
	v_add_f32_e32 v96, v96, v97
	v_add_f32_e32 v99, v114, v96
	ds_bpermute_b32 v108, v172, v99
	v_pk_mul_f32 v[96:97], v[168:169], v[100:101]
	v_pk_mul_f32 v[100:101], v[176:177], v[104:105]
	v_cvt_pk_bf16_f32 v98, v96, v97
	v_pk_mul_f32 v[102:103], v[170:171], v[102:103]
	s_waitcnt lgkmcnt(0)
	v_add_f32_e32 v96, v99, v108
	ds_bpermute_b32 v97, v173, v96
	v_pk_mul_f32 v[106:107], v[178:179], v[106:107]
	v_cvt_pk_bf16_f32 v99, v102, v103
	v_cvt_pk_bf16_f32 v100, v100, v101
	s_nop 0
	v_cvt_pk_bf16_f32 v101, v106, v107
	global_store_dwordx4 v[112:113], v[98:101], off offset:256 sc1
	s_and_saveexec_b64 s[76:77], s[42:43]
	s_cbranch_execz .LBB0_1435
	s_waitcnt lgkmcnt(0)
	v_add_f32_e32 v98, v96, v97
	v_add_u32_e32 v96, s70, v234
	v_ashrrev_i32_e32 v97, 31, v96
	s_lshl_b32 s52, s18, 2
	v_lshlrev_b64 v[96:97], 6, v[96:97]
	s_ashr_i32 s53, s52, 31
	v_lshl_add_u64 v[96:97], s[46:47], 0, v[96:97]
	v_lshl_add_u64 v[96:97], s[52:53], 2, v[96:97]
	s_lshl_b32 s8, s38, 2
	v_lshl_add_u64 v[96:97], v[96:97], 0, s[8:9]
	global_store_dword v[96:97], v98, off sc1

; __device__ __forceinline__ unsigned cvt_pk_bf16(float lo, float hi) { unsigned r; asm volatile("v_cvt_pk_bf16_f32 %0, %1, %2" : "=v"(r) : "v"(lo), "v"(hi)); return r; }
;     __device__ __forceinline__ void operator()(const f32x4 (&acc)[2][2][4][2], const Unit& u, int wr, int wc, int fr, int fq) const {
;     ...
;             for (int m = 0; m < 4; ++m) { const int rl = wr * 64 + fr + ai * HALF + m * 16; const size_t off = (size_t)rl * DM + col0; float sq = 0.f;
;                 bf16_t* hrow = h16 + (size_t)rowt * DM + off;
; #pragma unroll
;                 for (int bj = 0; bj < 2; ++bj) { f32x4 b0, b1;
;                     if (bb) { b0 = *(const f32x4*)(bb + off + bj * HALF); b1 = *(const f32x4*)(bb + off + bj * HALF + 4); }
;                     else { const u32x4 r = raw[m][bj];
;                         b0 = (f32x4){__uint_as_float(r.x << 16), __uint_as_float(r.x & 0xffff0000u), __uint_as_float(r.y << 16), __uint_as_float(r.y & 0xffff0000u)};
;                         b1 = (f32x4){__uint_as_float(r.z << 16), __uint_as_float(r.z & 0xffff0000u), __uint_as_float(r.w << 16), __uint_as_float(r.w & 0xffff0000u)}; }
;                     const f32x4 o0 = b0 + gv[bj][0] * acc[ai][bj][m][0], o1 = b1 + gv[bj][1] * acc[ai][bj][m][1];
;                     u32x4 w; w.x = cvt_pk_bf16(o0[0], o0[1]); w.y = cvt_pk_bf16(o0[2], o0[3]); w.z = cvt_pk_bf16(o1[0], o1[1]); w.w = cvt_pk_bf16(o1[2], o1[3]);
;                     *(u32x4*)(hrow + bj * HALF) = w;
;                     sq += ((o0[0] * o0[0] + o0[1] * o0[1]) + (o0[2] * o0[2] + o0[3] * o0[3])) + ((o1[0] * o1[0] + o1[1] * o1[1]) + (o1[2] * o1[2] + o1[3] * o1[3]));
;                     if (hb) { const f32x4 y0 = o0 * wv[bj][0], y1 = o1 * wv[bj][1]; u32x4 z; z.x = cvt_pk_bf16(y0[0], y0[1]); z.y = cvt_pk_bf16(y0[2], y0[3]); z.z = cvt_pk_bf16(y1[0], y1[1]); z.w = cvt_pk_bf16(y1[2], y1[3]);
;                         *(u32x4*)(hb + (size_t)rowt * DM + off + bj * HALF) = z; } }
;                 if (ssq) { sq += __shfl_xor(sq, 16); sq += __shfl_xor(sq, 32); if (fq == 0) ssq[(size_t)(rowt + rl) * 16 + u.pn * 4 + wc] = sq; } }
.LBB0_1441:
	v_mul_f32_e32 v101, v101, v101
	s_waitcnt vmcnt(0)
	v_pk_fma_f32 v[86:87], v[86:87], v[50:51], v[94:95]
	v_pk_fma_f32 v[84:85], v[84:85], v[48:49], v[92:93]
	v_pk_fma_f32 v[88:89], v[80:81], v[52:53], v[88:89]
	v_cvt_pk_bf16_f32 v80, v84, v85
	v_cvt_pk_bf16_f32 v81, v86, v87
	v_fmac_f32_e32 v101, v100, v100
	v_mul_f32_e32 v100, v103, v103
	v_pk_fma_f32 v[90:91], v[82:83], v[54:55], v[90:91]
	v_cvt_pk_bf16_f32 v82, v88, v89
	v_fmac_f32_e32 v100, v102, v102
	v_cvt_pk_bf16_f32 v83, v90, v91
	global_store_dwordx4 v[104:105], v[80:83], off offset:256 sc1
	v_add_f32_e32 v100, v101, v100
	v_mul_f32_e32 v101, v111, v111
	v_mul_f32_e32 v80, v85, v85
	v_mul_f32_e32 v81, v87, v87
	v_fmac_f32_e32 v80, v84, v84
	v_fmac_f32_e32 v81, v86, v86
	v_mul_f32_e32 v99, v99, v99
	v_add_f32_e32 v80, v80, v81
	v_mul_f32_e32 v81, v89, v89
	v_mul_f32_e32 v82, v91, v91
	v_fmac_f32_e32 v101, v110, v110
	v_fmac_f32_e32 v99, v98, v98
	v_fmac_f32_e32 v81, v88, v88
	v_fmac_f32_e32 v82, v90, v90
	v_add_f32_e32 v98, v101, v99
	v_add_f32_e32 v81, v81, v82
	v_add_f32_e32 v98, v100, v98
	v_add_f32_e32 v80, v80, v81
	v_add_f32_e32 v83, v98, v80
	ds_bpermute_b32 v92, v172, v83
	v_pk_mul_f32 v[80:81], v[168:169], v[84:85]
	v_pk_mul_f32 v[84:85], v[176:177], v[88:89]
	v_cvt_pk_bf16_f32 v82, v80, v81
	v_pk_mul_f32 v[86:87], v[170:171], v[86:87]
	s_waitcnt lgkmcnt(0)
	v_add_f32_e32 v80, v83, v92
	ds_bpermute_b32 v81, v173, v80
	v_pk_mul_f32 v[90:91], v[178:179], v[90:91]
	v_cvt_pk_bf16_f32 v83, v86, v87
	v_cvt_pk_bf16_f32 v84, v84, v85
	s_nop 0
	v_cvt_pk_bf16_f32 v85, v90, v91
	global_store_dwordx4 v[96:97], v[82:85], off offset:256 sc1
	s_and_saveexec_b64 s[76:77], s[42:43]
	s_cbranch_execz .LBB0_1443
	s_waitcnt lgkmcnt(0)
	v_add_f32_e32 v82, v80, v81
	v_add_u32_e32 v80, s70, v232
	v_ashrrev_i32_e32 v81, 31, v80
	s_lshl_b32 s52, s18, 2
	v_lshlrev_b64 v[80:81], 6, v[80:81]
	s_ashr_i32 s53, s52, 31
	v_lshl_add_u64 v[80:81], s[46:47], 0, v[80:81]
	v_lshl_add_u64 v[80:81], s[52:53], 2, v[80:81]
	s_lshl_b32 s8, s38, 2
	v_lshl_add_u64 v[80:81], v[80:81], 0, s[8:9]
	global_store_dword v[80:81], v82, off sc1

; __device__ __forceinline__ unsigned cvt_pk_bf16(float lo, float hi) { unsigned r; asm volatile("v_cvt_pk_bf16_f32 %0, %1, %2" : "=v"(r) : "v"(lo), "v"(hi)); return r; }
;     __device__ __forceinline__ void operator()(const f32x4 (&acc)[2][2][4][2], const Unit& u, int wr, int wc, int fr, int fq) const {
;     ...
;             for (int m = 0; m < 4; ++m) { const int rl = wr * 64 + fr + ai * HALF + m * 16; const size_t off = (size_t)rl * DM + col0; float sq = 0.f;
;                 bf16_t* hrow = h16 + (size_t)rowt * DM + off;
; #pragma unroll
;                 for (int bj = 0; bj < 2; ++bj) { f32x4 b0, b1;
;                     if (bb) { b0 = *(const f32x4*)(bb + off + bj * HALF); b1 = *(const f32x4*)(bb + off + bj * HALF + 4); }
;                     else { const u32x4 r = raw[m][bj];
;                         b0 = (f32x4){__uint_as_float(r.x << 16), __uint_as_float(r.x & 0xffff0000u), __uint_as_float(r.y << 16), __uint_as_float(r.y & 0xffff0000u)};
;                         b1 = (f32x4){__uint_as_float(r.z << 16), __uint_as_float(r.z & 0xffff0000u), __uint_as_float(r.w << 16), __uint_as_float(r.w & 0xffff0000u)}; }
;                     const f32x4 o0 = b0 + gv[bj][0] * acc[ai][bj][m][0], o1 = b1 + gv[bj][1] * acc[ai][bj][m][1];
;                     u32x4 w; w.x = cvt_pk_bf16(o0[0], o0[1]); w.y = cvt_pk_bf16(o0[2], o0[3]); w.z = cvt_pk_bf16(o1[0], o1[1]); w.w = cvt_pk_bf16(o1[2], o1[3]);
;                     *(u32x4*)(hrow + bj * HALF) = w;
;                     sq += ((o0[0] * o0[0] + o0[1] * o0[1]) + (o0[2] * o0[2] + o0[3] * o0[3])) + ((o1[0] * o1[0] + o1[1] * o1[1]) + (o1[2] * o1[2] + o1[3] * o1[3]));
;                     if (hb) { const f32x4 y0 = o0 * wv[bj][0], y1 = o1 * wv[bj][1]; u32x4 z; z.x = cvt_pk_bf16(y0[0], y0[1]); z.y = cvt_pk_bf16(y0[2], y0[3]); z.z = cvt_pk_bf16(y1[0], y1[1]); z.w = cvt_pk_bf16(y1[2], y1[3]);
;                         *(u32x4*)(hb + (size_t)rowt * DM + off + bj * HALF) = z; } }
;                 if (ssq) { sq += __shfl_xor(sq, 16); sq += __shfl_xor(sq, 32); if (fq == 0) ssq[(size_t)(rowt + rl) * 16 + u.pn * 4 + wc] = sq; } }
.LBB0_1449:
	s_waitcnt vmcnt(0)
	v_pk_fma_f32 v[62:63], v[62:63], v[50:51], v[78:79]
	v_pk_fma_f32 v[60:61], v[60:61], v[48:49], v[76:77]
	v_pk_fma_f32 v[72:73], v[56:57], v[52:53], v[72:73]
	v_cvt_pk_bf16_f32 v56, v60, v61
	v_cvt_pk_bf16_f32 v57, v62, v63
	v_mul_f32_e32 v104, v113, v113
	v_mul_f32_e32 v105, v115, v115
	v_pk_fma_f32 v[74:75], v[58:59], v[54:55], v[74:75]
	v_cvt_pk_bf16_f32 v58, v72, v73
	v_fmac_f32_e32 v104, v112, v112
	v_cvt_pk_bf16_f32 v59, v74, v75
	global_store_dwordx4 v[124:125], v[56:59], off offset:256 sc1
	v_fmac_f32_e32 v105, v114, v114
	v_add_f32_e32 v104, v104, v105
	v_mul_f32_e32 v56, v61, v61
	v_mul_f32_e32 v57, v63, v63
	v_fmac_f32_e32 v56, v60, v60
	v_fmac_f32_e32 v57, v62, v62
	v_mul_f32_e32 v105, v131, v131
	v_mul_f32_e32 v106, v111, v111
	v_add_f32_e32 v56, v56, v57
	v_mul_f32_e32 v57, v73, v73
	v_mul_f32_e32 v58, v75, v75
	v_fmac_f32_e32 v105, v130, v130
	v_fmac_f32_e32 v106, v110, v110
	v_fmac_f32_e32 v57, v72, v72
	v_fmac_f32_e32 v58, v74, v74
	v_add_f32_e32 v105, v105, v106
	v_add_f32_e32 v57, v57, v58
	v_add_f32_e32 v104, v104, v105
	v_add_f32_e32 v56, v56, v57
	v_add_f32_e32 v59, v104, v56
	ds_bpermute_b32 v76, v172, v59
	v_pk_mul_f32 v[56:57], v[168:169], v[60:61]
	v_pk_mul_f32 v[60:61], v[176:177], v[72:73]
	v_cvt_pk_bf16_f32 v58, v56, v57
	v_pk_mul_f32 v[62:63], v[170:171], v[62:63]
	s_waitcnt lgkmcnt(0)
	v_add_f32_e32 v56, v59, v76
	ds_bpermute_b32 v57, v173, v56
	v_pk_mul_f32 v[74:75], v[178:179], v[74:75]
	v_cvt_pk_bf16_f32 v59, v62, v63
	v_cvt_pk_bf16_f32 v60, v60, v61
	s_nop 0
	v_cvt_pk_bf16_f32 v61, v74, v75
	global_store_dwordx4 v[108:109], v[58:61], off offset:256 sc1
	s_and_saveexec_b64 s[76:77], s[42:43]
	s_cbranch_execz .LBB0_1451
	s_waitcnt lgkmcnt(0)
	v_add_f32_e32 v58, v56, v57
	v_add_u32_e32 v56, s70, v122
	v_ashrrev_i32_e32 v57, 31, v56
	s_lshl_b32 s52, s18, 2
	v_lshlrev_b64 v[56:57], 6, v[56:57]
	s_ashr_i32 s53, s52, 31
	v_lshl_add_u64 v[56:57], s[46:47], 0, v[56:57]
	v_lshl_add_u64 v[56:57], s[52:53], 2, v[56:57]
	s_lshl_b32 s8, s38, 2
	v_lshl_add_u64 v[56:57], v[56:57], 0, s[8:9]
	global_store_dword v[56:57], v58, off sc1

; __device__ __forceinline__ unsigned cvt_pk_bf16(float lo, float hi) { unsigned r; asm volatile("v_cvt_pk_bf16_f32 %0, %1, %2" : "=v"(r) : "v"(lo), "v"(hi)); return r; }
;     __device__ __forceinline__ void operator()(const f32x4 (&acc)[2][2][4][2], const Unit& u, int wr, int wc, int fr, int fq) const {
;     ...
;             for (int m = 0; m < 4; ++m) { const int rl = wr * 64 + fr + ai * HALF + m * 16; const size_t off = (size_t)rl * DM + col0; float sq = 0.f;
;                 bf16_t* hrow = h16 + (size_t)rowt * DM + off;
; #pragma unroll
;                 for (int bj = 0; bj < 2; ++bj) { f32x4 b0, b1;
;                     if (bb) { b0 = *(const f32x4*)(bb + off + bj * HALF); b1 = *(const f32x4*)(bb + off + bj * HALF + 4); }
;                     else { const u32x4 r = raw[m][bj];
;                         b0 = (f32x4){__uint_as_float(r.x << 16), __uint_as_float(r.x & 0xffff0000u), __uint_as_float(r.y << 16), __uint_as_float(r.y & 0xffff0000u)};
;                         b1 = (f32x4){__uint_as_float(r.z << 16), __uint_as_float(r.z & 0xffff0000u), __uint_as_float(r.w << 16), __uint_as_float(r.w & 0xffff0000u)}; }
;                     const f32x4 o0 = b0 + gv[bj][0] * acc[ai][bj][m][0], o1 = b1 + gv[bj][1] * acc[ai][bj][m][1];
;                     u32x4 w; w.x = cvt_pk_bf16(o0[0], o0[1]); w.y = cvt_pk_bf16(o0[2], o0[3]); w.z = cvt_pk_bf16(o1[0], o1[1]); w.w = cvt_pk_bf16(o1[2], o1[3]);
;                     *(u32x4*)(hrow + bj * HALF) = w;
;                     sq += ((o0[0] * o0[0] + o0[1] * o0[1]) + (o0[2] * o0[2] + o0[3] * o0[3])) + ((o1[0] * o1[0] + o1[1] * o1[1]) + (o1[2] * o1[2] + o1[3] * o1[3]));
;                     if (hb) { const f32x4 y0 = o0 * wv[bj][0], y1 = o1 * wv[bj][1]; u32x4 z; z.x = cvt_pk_bf16(y0[0], y0[1]); z.y = cvt_pk_bf16(y0[2], y0[3]); z.z = cvt_pk_bf16(y1[0], y1[1]); z.w = cvt_pk_bf16(y1[2], y1[3]);
;                         *(u32x4*)(hb + (size_t)rowt * DM + off + bj * HALF) = z; } }
;                 if (ssq) { sq += __shfl_xor(sq, 16); sq += __shfl_xor(sq, 32); if (fq == 0) ssq[(size_t)(rowt + rl) * 16 + u.pn * 4 + wc] = sq; } }
.LBB0_1457:
	v_mul_f32_e32 v61, v61, v61
	s_waitcnt vmcnt(0)
	v_pk_fma_f32 v[38:39], v[38:39], v[50:51], v[46:47]
	v_pk_fma_f32 v[36:37], v[36:37], v[48:49], v[44:45]
	v_pk_fma_f32 v[40:41], v[32:33], v[52:53], v[40:41]
	v_cvt_pk_bf16_f32 v32, v36, v37
	v_cvt_pk_bf16_f32 v33, v38, v39
	v_fmac_f32_e32 v61, v60, v60
	v_mul_f32_e32 v60, v63, v63
	v_pk_fma_f32 v[42:43], v[34:35], v[54:55], v[42:43]
	v_cvt_pk_bf16_f32 v34, v40, v41
	v_fmac_f32_e32 v60, v62, v62
	v_cvt_pk_bf16_f32 v35, v42, v43
	global_store_dwordx4 v[72:73], v[32:35], off offset:256 sc1
	v_add_f32_e32 v60, v61, v60
	v_mul_f32_e32 v61, v79, v79
	v_mul_f32_e32 v32, v37, v37
	v_mul_f32_e32 v33, v39, v39
	v_fmac_f32_e32 v32, v36, v36
	v_fmac_f32_e32 v33, v38, v38
	v_mul_f32_e32 v59, v59, v59
	v_add_f32_e32 v32, v32, v33
	v_mul_f32_e32 v33, v41, v41
	v_mul_f32_e32 v34, v43, v43
	v_fmac_f32_e32 v61, v78, v78
	v_fmac_f32_e32 v59, v58, v58
	v_fmac_f32_e32 v33, v40, v40
	v_fmac_f32_e32 v34, v42, v42
	v_add_f32_e32 v58, v61, v59
	v_add_f32_e32 v33, v33, v34
	v_add_f32_e32 v58, v60, v58
	v_add_f32_e32 v32, v32, v33
	v_add_f32_e32 v35, v58, v32
	ds_bpermute_b32 v44, v172, v35
	v_pk_mul_f32 v[32:33], v[168:169], v[36:37]
	v_pk_mul_f32 v[36:37], v[176:177], v[40:41]
	v_cvt_pk_bf16_f32 v34, v32, v33
	v_pk_mul_f32 v[38:39], v[170:171], v[38:39]
	s_waitcnt lgkmcnt(0)
	v_add_f32_e32 v32, v35, v44
	ds_bpermute_b32 v33, v173, v32
	v_pk_mul_f32 v[42:43], v[178:179], v[42:43]
	v_cvt_pk_bf16_f32 v35, v38, v39
	v_cvt_pk_bf16_f32 v36, v36, v37
	s_nop 0
	v_cvt_pk_bf16_f32 v37, v42, v43
	global_store_dwordx4 v[56:57], v[34:37], off offset:256 sc1
	s_and_saveexec_b64 s[76:77], s[42:43]
	s_cbranch_execz .LBB0_1459
	s_waitcnt lgkmcnt(0)
	v_add_f32_e32 v34, v32, v33
	v_add_u32_e32 v32, s70, v120
	v_ashrrev_i32_e32 v33, 31, v32
	s_lshl_b32 s52, s18, 2
	v_lshlrev_b64 v[32:33], 6, v[32:33]
	s_ashr_i32 s53, s52, 31
	v_lshl_add_u64 v[32:33], s[46:47], 0, v[32:33]
	v_lshl_add_u64 v[32:33], s[52:53], 2, v[32:33]
	s_lshl_b32 s8, s38, 2
	v_lshl_add_u64 v[32:33], v[32:33], 0, s[8:9]
	global_store_dword v[32:33], v34, off sc1

; __device__ __forceinline__ unsigned cvt_pk_bf16(float lo, float hi) { unsigned r; asm volatile("v_cvt_pk_bf16_f32 %0, %1, %2" : "=v"(r) : "v"(lo), "v"(hi)); return r; }
;     __device__ __forceinline__ void operator()(const f32x4 (&acc)[2][2][4][2], const Unit& u, int wr, int wc, int fr, int fq) const {
;     ...
;             for (int m = 0; m < 4; ++m) { const int rl = wr * 64 + fr + ai * HALF + m * 16; const size_t off = (size_t)rl * DM + col0; float sq = 0.f;
;                 bf16_t* hrow = h16 + (size_t)rowt * DM + off;
; #pragma unroll
;                 for (int bj = 0; bj < 2; ++bj) { f32x4 b0, b1;
;                     if (bb) { b0 = *(const f32x4*)(bb + off + bj * HALF); b1 = *(const f32x4*)(bb + off + bj * HALF + 4); }
;                     else { const u32x4 r = raw[m][bj];
;                         b0 = (f32x4){__uint_as_float(r.x << 16), __uint_as_float(r.x & 0xffff0000u), __uint_as_float(r.y << 16), __uint_as_float(r.y & 0xffff0000u)};
;                         b1 = (f32x4){__uint_as_float(r.z << 16), __uint_as_float(r.z & 0xffff0000u), __uint_as_float(r.w << 16), __uint_as_float(r.w & 0xffff0000u)}; }
;                     const f32x4 o0 = b0 + gv[bj][0] * acc[ai][bj][m][0], o1 = b1 + gv[bj][1] * acc[ai][bj][m][1];
;                     u32x4 w; w.x = cvt_pk_bf16(o0[0], o0[1]); w.y = cvt_pk_bf16(o0[2], o0[3]); w.z = cvt_pk_bf16(o1[0], o1[1]); w.w = cvt_pk_bf16(o1[2], o1[3]);
;                     *(u32x4*)(hrow + bj * HALF) = w;
;                     sq += ((o0[0] * o0[0] + o0[1] * o0[1]) + (o0[2] * o0[2] + o0[3] * o0[3])) + ((o1[0] * o1[0] + o1[1] * o1[1]) + (o1[2] * o1[2] + o1[3] * o1[3]));
;                     if (hb) { const f32x4 y0 = o0 * wv[bj][0], y1 = o1 * wv[bj][1]; u32x4 z; z.x = cvt_pk_bf16(y0[0], y0[1]); z.y = cvt_pk_bf16(y0[2], y0[3]); z.z = cvt_pk_bf16(y1[0], y1[1]); z.w = cvt_pk_bf16(y1[2], y1[3]);
;                         *(u32x4*)(hb + (size_t)rowt * DM + off + bj * HALF) = z; } }
;                 if (ssq) { sq += __shfl_xor(sq, 16); sq += __shfl_xor(sq, 32); if (fq == 0) ssq[(size_t)(rowt + rl) * 16 + u.pn * 4 + wc] = sq; } }
.LBB0_1465:
	v_mul_f32_e32 v37, v37, v37
	s_waitcnt vmcnt(0)
	v_pk_fma_f32 v[22:23], v[22:23], v[50:51], v[30:31]
	v_pk_fma_f32 v[20:21], v[20:21], v[48:49], v[28:29]
	v_pk_fma_f32 v[24:25], v[16:17], v[52:53], v[24:25]
	v_cvt_pk_bf16_f32 v16, v20, v21
	v_cvt_pk_bf16_f32 v17, v22, v23
	v_fmac_f32_e32 v37, v36, v36
	v_mul_f32_e32 v36, v39, v39
	v_pk_fma_f32 v[26:27], v[18:19], v[54:55], v[26:27]
	v_cvt_pk_bf16_f32 v18, v24, v25
	v_fmac_f32_e32 v36, v38, v38
	v_cvt_pk_bf16_f32 v19, v26, v27
	global_store_dwordx4 v[40:41], v[16:19], off offset:256 sc1
	v_add_f32_e32 v36, v37, v36
	v_mul_f32_e32 v37, v47, v47
	v_mul_f32_e32 v16, v21, v21
	v_mul_f32_e32 v17, v23, v23
	v_fmac_f32_e32 v16, v20, v20
	v_fmac_f32_e32 v17, v22, v22
	v_mul_f32_e32 v35, v35, v35
	v_add_f32_e32 v16, v16, v17
	v_mul_f32_e32 v17, v25, v25
	v_mul_f32_e32 v18, v27, v27
	v_fmac_f32_e32 v37, v46, v46
	v_fmac_f32_e32 v35, v34, v34
	v_fmac_f32_e32 v17, v24, v24
	v_fmac_f32_e32 v18, v26, v26
	v_add_f32_e32 v34, v37, v35
	v_add_f32_e32 v17, v17, v18
	v_add_f32_e32 v34, v36, v34
	v_add_f32_e32 v16, v16, v17
	v_add_f32_e32 v19, v34, v16
	ds_bpermute_b32 v28, v172, v19
	v_pk_mul_f32 v[16:17], v[168:169], v[20:21]
	v_pk_mul_f32 v[20:21], v[176:177], v[24:25]
	v_cvt_pk_bf16_f32 v18, v16, v17
	v_pk_mul_f32 v[22:23], v[170:171], v[22:23]
	s_waitcnt lgkmcnt(0)
	v_add_f32_e32 v16, v19, v28
	ds_bpermute_b32 v17, v173, v16
	v_pk_mul_f32 v[26:27], v[178:179], v[26:27]
	v_cvt_pk_bf16_f32 v19, v22, v23
	v_cvt_pk_bf16_f32 v20, v20, v21
	s_nop 0
	v_cvt_pk_bf16_f32 v21, v26, v27
	global_store_dwordx4 v[32:33], v[18:21], off offset:256 sc1
	s_and_saveexec_b64 s[76:77], s[42:43]
	s_cbranch_execz .LBB0_1467
	s_waitcnt lgkmcnt(0)
	v_add_f32_e32 v18, v16, v17
	v_add_u32_e32 v16, s70, v118
	v_ashrrev_i32_e32 v17, 31, v16
	s_lshl_b32 s52, s18, 2
	v_lshlrev_b64 v[16:17], 6, v[16:17]
	s_ashr_i32 s53, s52, 31
	v_lshl_add_u64 v[16:17], s[46:47], 0, v[16:17]
	v_lshl_add_u64 v[16:17], s[52:53], 2, v[16:17]
	s_lshl_b32 s8, s38, 2
	v_lshl_add_u64 v[16:17], v[16:17], 0, s[8:9]
	global_store_dword v[16:17], v18, off sc1

; __device__ __forceinline__ unsigned cvt_pk_bf16(float lo, float hi) { unsigned r; asm volatile("v_cvt_pk_bf16_f32 %0, %1, %2" : "=v"(r) : "v"(lo), "v"(hi)); return r; }
;     __device__ __forceinline__ void operator()(const f32x4 (&acc)[2][2][4][2], const Unit& u, int wr, int wc, int fr, int fq) const {
;     ...
;             for (int m = 0; m < 4; ++m) { const int rl = wr * 64 + fr + ai * HALF + m * 16; const size_t off = (size_t)rl * DM + col0; float sq = 0.f;
;                 bf16_t* hrow = h16 + (size_t)rowt * DM + off;
; #pragma unroll
;                 for (int bj = 0; bj < 2; ++bj) { f32x4 b0, b1;
;                     if (bb) { b0 = *(const f32x4*)(bb + off + bj * HALF); b1 = *(const f32x4*)(bb + off + bj * HALF + 4); }
;                     else { const u32x4 r = raw[m][bj];
;                         b0 = (f32x4){__uint_as_float(r.x << 16), __uint_as_float(r.x & 0xffff0000u), __uint_as_float(r.y << 16), __uint_as_float(r.y & 0xffff0000u)};
;                         b1 = (f32x4){__uint_as_float(r.z << 16), __uint_as_float(r.z & 0xffff0000u), __uint_as_float(r.w << 16), __uint_as_float(r.w & 0xffff0000u)}; }
;                     const f32x4 o0 = b0 + gv[bj][0] * acc[ai][bj][m][0], o1 = b1 + gv[bj][1] * acc[ai][bj][m][1];
;                     u32x4 w; w.x = cvt_pk_bf16(o0[0], o0[1]); w.y = cvt_pk_bf16(o0[2], o0[3]); w.z = cvt_pk_bf16(o1[0], o1[1]); w.w = cvt_pk_bf16(o1[2], o1[3]);
;                     *(u32x4*)(hrow + bj * HALF) = w;
;                     sq += ((o0[0] * o0[0] + o0[1] * o0[1]) + (o0[2] * o0[2] + o0[3] * o0[3])) + ((o1[0] * o1[0] + o1[1] * o1[1]) + (o1[2] * o1[2] + o1[3] * o1[3]));
;                     if (hb) { const f32x4 y0 = o0 * wv[bj][0], y1 = o1 * wv[bj][1]; u32x4 z; z.x = cvt_pk_bf16(y0[0], y0[1]); z.y = cvt_pk_bf16(y0[2], y0[3]); z.z = cvt_pk_bf16(y1[0], y1[1]); z.w = cvt_pk_bf16(y1[2], y1[3]);
;                         *(u32x4*)(hb + (size_t)rowt * DM + off + bj * HALF) = z; } }
;                 if (ssq) { sq += __shfl_xor(sq, 16); sq += __shfl_xor(sq, 32); if (fq == 0) ssq[(size_t)(rowt + rl) * 16 + u.pn * 4 + wc] = sq; } }
.LBB0_1473:
	v_mul_f32_e32 v21, v21, v21
	s_waitcnt vmcnt(0)
	v_pk_fma_f32 v[6:7], v[6:7], v[50:51], v[14:15]
	v_pk_fma_f32 v[4:5], v[4:5], v[48:49], v[12:13]
	v_pk_fma_f32 v[8:9], v[0:1], v[52:53], v[8:9]
	v_cvt_pk_bf16_f32 v0, v4, v5
	v_cvt_pk_bf16_f32 v1, v6, v7
	v_fmac_f32_e32 v21, v20, v20
	v_mul_f32_e32 v20, v23, v23
	v_pk_fma_f32 v[10:11], v[2:3], v[54:55], v[10:11]
	v_cvt_pk_bf16_f32 v2, v8, v9
	v_fmac_f32_e32 v20, v22, v22
	v_cvt_pk_bf16_f32 v3, v10, v11
	global_store_dwordx4 v[24:25], v[0:3], off offset:256 sc1
	v_add_f32_e32 v20, v21, v20
	v_mul_f32_e32 v21, v31, v31
	v_mul_f32_e32 v0, v5, v5
	v_mul_f32_e32 v1, v7, v7
	v_fmac_f32_e32 v0, v4, v4
	v_fmac_f32_e32 v1, v6, v6
	v_mul_f32_e32 v19, v19, v19
	v_add_f32_e32 v0, v0, v1
	v_mul_f32_e32 v1, v9, v9
	v_mul_f32_e32 v2, v11, v11
	v_fmac_f32_e32 v21, v30, v30
	v_fmac_f32_e32 v19, v18, v18
	v_fmac_f32_e32 v1, v8, v8
	v_fmac_f32_e32 v2, v10, v10
	v_add_f32_e32 v18, v21, v19
	v_add_f32_e32 v1, v1, v2
	v_add_f32_e32 v18, v20, v18
	v_add_f32_e32 v0, v0, v1
	v_add_f32_e32 v3, v18, v0
	ds_bpermute_b32 v12, v172, v3
	v_pk_mul_f32 v[0:1], v[168:169], v[4:5]
	v_pk_mul_f32 v[4:5], v[176:177], v[8:9]
	v_cvt_pk_bf16_f32 v2, v0, v1
	v_pk_mul_f32 v[6:7], v[170:171], v[6:7]
	s_waitcnt lgkmcnt(0)
	v_add_f32_e32 v0, v3, v12
	ds_bpermute_b32 v1, v173, v0
	v_pk_mul_f32 v[10:11], v[178:179], v[10:11]
	v_cvt_pk_bf16_f32 v3, v6, v7
	v_cvt_pk_bf16_f32 v4, v4, v5
	s_nop 0
	v_cvt_pk_bf16_f32 v5, v10, v11
	global_store_dwordx4 v[16:17], v[2:5], off offset:256 sc1
	s_and_saveexec_b64 s[44:45], s[42:43]
	s_cbranch_execz .LBB0_1475
	s_waitcnt lgkmcnt(0)
	v_add_f32_e32 v2, v0, v1
	v_add_u32_e32 v0, s70, v116
	v_ashrrev_i32_e32 v1, 31, v0
	s_lshl_b32 s18, s18, 2
	v_lshlrev_b64 v[0:1], 6, v[0:1]
	s_ashr_i32 s19, s18, 31
	v_lshl_add_u64 v[0:1], s[46:47], 0, v[0:1]
	v_lshl_add_u64 v[0:1], s[18:19], 2, v[0:1]
	s_lshl_b32 s8, s38, 2
	v_lshl_add_u64 v[0:1], v[0:1], 0, s[8:9]
	global_store_dword v[0:1], v2, off sc1

.LBB0_1598:
	v_readlane_b32 s0, v254, 2
	s_add_i32 s74, s0, 2
	s_cmp_ge_i32 s74, s81
	s_cbranch_scc1 .LBB0_1681
	v_readlane_b32 s100, v255, 8
	s_cmp_eq_u32 s100, 3
	s_cbranch_scc0 .Lgs_orig_3
	s_waitcnt vmcnt(0) lgkmcnt(0)
	s_barrier
	v_readlane_b32 s100, v255, 59
	s_add_i32 s100, s100, 1
	v_writelane_b32 v255, s100, 59
	v_cmp_eq_u32_e32 vcc, 0, v215
	s_and_saveexec_b64 s[0:1], vcc
	s_cbranch_execz .Lgs_w_3
	s_load_dwordx2 s[2:3], s[94:95], 0xb8
	v_readlane_b32 s101, v255, 12
	s_and_b32 s101, s101, 63
	s_lshl_b32 s101, s101, 6
	s_cmp_lt_u32 s101, 0x800
	s_movk_i32 s7, 0x1400
	s_cselect_b32 s7, 0xc00, s7
	s_add_i32 s101, s101, s7
	s_lshl_b32 s100, s100, 2
	v_mov_b32_e32 v0, s101
	v_mov_b32_e32 v1, 1
	s_waitcnt lgkmcnt(0)
	s_add_u32 s2, s2, 0xe0000
	s_addc_u32 s3, s3, 0
	global_atomic_add v0, v1, s[2:3]
	buffer_inv sc1
	s_mov_b32 s6, 0

.LBB0_1776:
	s_add_i32 s4, s74, 1
	s_cmp_ge_i32 s4, s81
	s_cbranch_scc1 .LBB0_1842
	v_readlane_b32 s100, v255, 8
	s_cmp_lg_u32 s100, 0
	s_cbranch_scc0 .Lgs_orig_4
	s_waitcnt vmcnt(0) lgkmcnt(0)
	s_barrier
	v_readlane_b32 s100, v255, 59
	s_add_i32 s100, s100, 1
	v_writelane_b32 v255, s100, 59
	v_cmp_eq_u32_e32 vcc, 0, v215
	s_and_saveexec_b64 s[0:1], vcc
	s_cbranch_execz .Lgs_w_4
	s_load_dwordx2 s[2:3], s[94:95], 0xb8
	v_readlane_b32 s101, v255, 12
	s_and_b32 s101, s101, 63
	s_lshl_b32 s101, s101, 6
	s_cmp_lt_u32 s101, 0x800
	s_movk_i32 s7, 0x1400
	s_cselect_b32 s7, 0xc00, s7
	s_add_i32 s101, s101, s7
	s_lshl_b32 s100, s100, 2
	v_mov_b32_e32 v0, s101
	v_mov_b32_e32 v1, 1
	s_waitcnt lgkmcnt(0)
	s_add_u32 s2, s2, 0xe0000
	s_addc_u32 s3, s3, 0
	global_atomic_add v0, v1, s[2:3]
	buffer_inv sc1
	s_mov_b32 s6, 0

; __device__ __forceinline__ unsigned xb_add(unsigned* p, unsigned v) { return __hip_atomic_fetch_add(p, v, __ATOMIC_RELAXED, __HIP_MEMORY_SCOPE_AGENT); }
; __device__ __forceinline__ void xcd_barrier(const XcdBarrier& b, int tid) {
;     asm volatile("s_waitcnt vmcnt(0)" ::: "memory");
;     __syncthreads();
;     if (tid == 0) {
;         unsigned* bar = b.bar;
;         __builtin_amdgcn_s_waitcnt(0);
;         unsigned nloc = b.st[0], nx = b.st[1];
;         if (nloc == 0u) { xcd_barrier_complete(bar, b.x, nloc, nx); b.st[0] = nloc; b.st[1] = nx; }
;         const unsigned old = xb_add(&bar[XB_XSUB(b.x)], 1u);
.Lgs_orig_4:
	v_readlane_b32 s0, v254, 3
	v_readlane_b32 s1, v254, 4
	s_andn2_b64 vcc, exec, s[0:1]
	s_cbranch_vccnz .LBB0_1789
	s_waitcnt vmcnt(0) lgkmcnt(0)
	s_barrier
	s_mov_b64 s[0:1], exec
	v_readlane_b32 s2, v255, 6
	v_readlane_b32 s3, v255, 7
	s_and_b64 s[2:3], s[0:1], s[2:3]
	s_mov_b64 exec, s[2:3]
	s_cbranch_execz .LBB0_1788
	v_readlane_b32 s2, v254, 0
	v_readlane_b32 s3, v254, 1
	buffer_wbl2 sc1
	s_load_dwordx2 s[2:3], s[2:3], 0x58
	s_mov_b64 s[6:7], exec
	v_mbcnt_lo_u32_b32 v1, s6, 0
	v_mbcnt_hi_u32_b32 v1, s7, v1
	v_cmp_eq_u32_e32 vcc, 0, v1
	s_waitcnt lgkmcnt(0)
	global_load_dword v0, v213, s[2:3] offset:40
	s_and_saveexec_b64 s[12:13], vcc
	s_cbranch_execz .LBB0_1781
	s_bcnt1_i32_b64 s5, s[6:7]
	v_mov_b32_e32 v2, s5
	global_atomic_add v2, v213, v2, s[2:3] offset:32 sc0

; __device__ __forceinline__ unsigned cvt_pk_bf16(float lo, float hi) { unsigned r; asm volatile("v_cvt_pk_bf16_f32 %0, %1, %2" : "=v"(r) : "v"(lo), "v"(hi)); return r; }
;     __device__ __forceinline__ void operator()(const f32x4 (&acc)[2][2][4][2], const Unit& u, int wr, int wc, int fr, int fq) const {
;     ...
;                     sq += ((o0[0] * o0[0] + o0[1] * o0[1]) + (o0[2] * o0[2] + o0[3] * o0[3])) + ((o1[0] * o1[0] + o1[1] * o1[1]) + (o1[2] * o1[2] + o1[3] * o1[3]));
;                     if (hb) { const f32x4 y0 = o0 * wv[bj][0], y1 = o1 * wv[bj][1]; u32x4 z; z.x = cvt_pk_bf16(y0[0], y0[1]); z.y = cvt_pk_bf16(y0[2], y0[3]); z.z = cvt_pk_bf16(y1[0], y1[1]); z.w = cvt_pk_bf16(y1[2], y1[3]);
;                         *(u32x4*)(hb + (size_t)rowt * DM + off + bj * HALF) = z; } }
;                 if (ssq) { sq += __shfl_xor(sq, 16); sq += __shfl_xor(sq, 32); if (fq == 0) ssq[(size_t)(rowt + rl) * 16 + u.pn * 4 + wc] = sq; } }
.LBB0_1880:
	v_mul_f32_e32 v129, v129, v129
	v_mul_f32_e32 v141, v141, v141
	v_mul_f32_e32 v137, v137, v137
	v_mul_f32_e32 v133, v133, v133
	v_fmac_f32_e32 v129, v128, v128
	v_mul_f32_e32 v128, v131, v131
	v_fmac_f32_e32 v141, v140, v140
	v_mul_f32_e32 v140, v143, v143
	v_fmac_f32_e32 v137, v136, v136
	v_mul_f32_e32 v136, v139, v139
	v_fmac_f32_e32 v133, v132, v132
	v_mul_f32_e32 v132, v135, v135
	v_fmac_f32_e32 v128, v130, v130
	v_and_b32_e32 v130, 64, v246
	v_fmac_f32_e32 v140, v142, v142
	v_fmac_f32_e32 v136, v138, v138
	v_fmac_f32_e32 v132, v134, v134
	v_add_f32_e32 v128, v129, v128
	v_xor_b32_e32 v129, 16, v246
	v_add_u32_e32 v131, 64, v130
	v_add_f32_e32 v140, v141, v140
	v_add_f32_e32 v136, v137, v136
	v_add_f32_e32 v132, v133, v132
	v_cmp_lt_i32_e32 vcc, v129, v131
	v_add_f32_e32 v136, v140, v136
	v_add_f32_e32 v128, v132, v128
	v_cndmask_b32_e32 v129, v246, v129, vcc
	v_add_f32_e32 v128, v128, v136
	v_lshlrev_b32_e32 v130, 2, v129
	ds_bpermute_b32 v129, v130, v128
	v_cmp_eq_u32_e64 s[42:43], 0, v233
	s_waitcnt lgkmcnt(0)
	v_add_f32_e32 v128, v128, v129
	v_xor_b32_e32 v129, 32, v246
	v_cmp_lt_i32_e32 vcc, v129, v131
	s_nop 1
	v_cndmask_b32_e32 v129, v246, v129, vcc
	v_lshlrev_b32_e32 v131, 2, v129
	ds_bpermute_b32 v129, v131, v128
	s_and_saveexec_b64 s[58:59], s[42:43]
	s_cbranch_execz .LBB0_1882
	s_waitcnt lgkmcnt(0)
	v_add_f32_e32 v132, v128, v129
	v_add_u32_e32 v128, s48, v200
	v_ashrrev_i32_e32 v129, 31, v128
	s_lshl_b32 s52, s0, 2
	v_lshlrev_b64 v[128:129], 6, v[128:129]
	s_ashr_i32 s53, s52, 31
	v_lshl_add_u64 v[128:129], s[14:15], 0, v[128:129]
	v_lshl_add_u64 v[128:129], s[52:53], 2, v[128:129]
	s_lshl_b32 s8, s69, 2
	v_lshl_add_u64 v[128:129], v[128:129], 0, s[8:9]
	global_store_dword v[128:129], v132, off sc1

; __device__ __forceinline__ unsigned cvt_pk_bf16(float lo, float hi) { unsigned r; asm volatile("v_cvt_pk_bf16_f32 %0, %1, %2" : "=v"(r) : "v"(lo), "v"(hi)); return r; }
;     __device__ __forceinline__ void operator()(const f32x4 (&acc)[2][2][4][2], const Unit& u, int wr, int wc, int fr, int fq) const {
;     ...
;                     sq += ((o0[0] * o0[0] + o0[1] * o0[1]) + (o0[2] * o0[2] + o0[3] * o0[3])) + ((o1[0] * o1[0] + o1[1] * o1[1]) + (o1[2] * o1[2] + o1[3] * o1[3]));
;                     if (hb) { const f32x4 y0 = o0 * wv[bj][0], y1 = o1 * wv[bj][1]; u32x4 z; z.x = cvt_pk_bf16(y0[0], y0[1]); z.y = cvt_pk_bf16(y0[2], y0[3]); z.z = cvt_pk_bf16(y1[0], y1[1]); z.w = cvt_pk_bf16(y1[2], y1[3]);
;                         *(u32x4*)(hb + (size_t)rowt * DM + off + bj * HALF) = z; } }
;                 if (ssq) { sq += __shfl_xor(sq, 16); sq += __shfl_xor(sq, 32); if (fq == 0) ssq[(size_t)(rowt + rl) * 16 + u.pn * 4 + wc] = sq; } }
.LBB0_1886:
	v_mul_f32_e32 v125, v125, v125
	v_mul_f32_e32 v121, v121, v121
	v_mul_f32_e32 v117, v117, v117
	v_mul_f32_e32 v113, v113, v113
	v_fmac_f32_e32 v125, v124, v124
	v_mul_f32_e32 v124, v127, v127
	v_fmac_f32_e32 v121, v120, v120
	v_mul_f32_e32 v120, v123, v123
	v_fmac_f32_e32 v117, v116, v116
	v_mul_f32_e32 v116, v119, v119
	v_fmac_f32_e32 v113, v112, v112
	v_mul_f32_e32 v112, v115, v115
	v_fmac_f32_e32 v124, v126, v126
	v_fmac_f32_e32 v120, v122, v122
	v_fmac_f32_e32 v116, v118, v118
	v_fmac_f32_e32 v112, v114, v114
	v_add_f32_e32 v124, v125, v124
	v_add_f32_e32 v120, v121, v120
	v_add_f32_e32 v116, v117, v116
	v_add_f32_e32 v112, v113, v112
	v_add_f32_e32 v120, v124, v120
	v_add_f32_e32 v112, v116, v112
	v_add_f32_e32 v112, v120, v112
	ds_bpermute_b32 v113, v130, v112
	s_waitcnt lgkmcnt(0)
	v_add_f32_e32 v112, v112, v113
	ds_bpermute_b32 v113, v131, v112
	s_and_saveexec_b64 s[58:59], s[42:43]
	s_cbranch_execz .LBB0_1888
	s_waitcnt lgkmcnt(0)
	v_add_f32_e32 v114, v112, v113
	v_add_u32_e32 v112, s48, v220
	v_ashrrev_i32_e32 v113, 31, v112
	s_lshl_b32 s52, s0, 2
	v_lshlrev_b64 v[112:113], 6, v[112:113]
	s_ashr_i32 s53, s52, 31
	v_lshl_add_u64 v[112:113], s[14:15], 0, v[112:113]
	v_lshl_add_u64 v[112:113], s[52:53], 2, v[112:113]
	s_lshl_b32 s8, s69, 2
	v_lshl_add_u64 v[112:113], v[112:113], 0, s[8:9]
	global_store_dword v[112:113], v114, off sc1

; __device__ __forceinline__ unsigned cvt_pk_bf16(float lo, float hi) { unsigned r; asm volatile("v_cvt_pk_bf16_f32 %0, %1, %2" : "=v"(r) : "v"(lo), "v"(hi)); return r; }
;     __device__ __forceinline__ void operator()(const f32x4 (&acc)[2][2][4][2], const Unit& u, int wr, int wc, int fr, int fq) const {
;     ...
;                     sq += ((o0[0] * o0[0] + o0[1] * o0[1]) + (o0[2] * o0[2] + o0[3] * o0[3])) + ((o1[0] * o1[0] + o1[1] * o1[1]) + (o1[2] * o1[2] + o1[3] * o1[3]));
;                     if (hb) { const f32x4 y0 = o0 * wv[bj][0], y1 = o1 * wv[bj][1]; u32x4 z; z.x = cvt_pk_bf16(y0[0], y0[1]); z.y = cvt_pk_bf16(y0[2], y0[3]); z.z = cvt_pk_bf16(y1[0], y1[1]); z.w = cvt_pk_bf16(y1[2], y1[3]);
;                         *(u32x4*)(hb + (size_t)rowt * DM + off + bj * HALF) = z; } }
;                 if (ssq) { sq += __shfl_xor(sq, 16); sq += __shfl_xor(sq, 32); if (fq == 0) ssq[(size_t)(rowt + rl) * 16 + u.pn * 4 + wc] = sq; } }
.LBB0_1892:
	v_mul_f32_e32 v109, v109, v109
	v_mul_f32_e32 v105, v105, v105
	v_mul_f32_e32 v101, v101, v101
	v_mul_f32_e32 v97, v97, v97
	v_fmac_f32_e32 v109, v108, v108
	v_mul_f32_e32 v108, v111, v111
	v_fmac_f32_e32 v105, v104, v104
	v_mul_f32_e32 v104, v107, v107
	v_fmac_f32_e32 v101, v100, v100
	v_mul_f32_e32 v100, v103, v103
	v_fmac_f32_e32 v97, v96, v96
	v_mul_f32_e32 v96, v99, v99
	v_fmac_f32_e32 v108, v110, v110
	v_fmac_f32_e32 v104, v106, v106
	v_fmac_f32_e32 v100, v102, v102
	v_fmac_f32_e32 v96, v98, v98
	v_add_f32_e32 v108, v109, v108
	v_add_f32_e32 v104, v105, v104
	v_add_f32_e32 v100, v101, v100
	v_add_f32_e32 v96, v97, v96
	v_add_f32_e32 v104, v108, v104
	v_add_f32_e32 v96, v100, v96
	v_add_f32_e32 v96, v104, v96
	ds_bpermute_b32 v97, v130, v96
	s_waitcnt lgkmcnt(0)
	v_add_f32_e32 v96, v96, v97
	ds_bpermute_b32 v97, v131, v96
	s_and_saveexec_b64 s[58:59], s[42:43]
	s_cbranch_execz .LBB0_1894
	s_waitcnt lgkmcnt(0)
	v_add_f32_e32 v98, v96, v97
	v_add_u32_e32 v96, s48, v208
	v_ashrrev_i32_e32 v97, 31, v96
	s_lshl_b32 s52, s0, 2
	v_lshlrev_b64 v[96:97], 6, v[96:97]
	s_ashr_i32 s53, s52, 31
	v_lshl_add_u64 v[96:97], s[14:15], 0, v[96:97]
	v_lshl_add_u64 v[96:97], s[52:53], 2, v[96:97]
	s_lshl_b32 s8, s69, 2
	v_lshl_add_u64 v[96:97], v[96:97], 0, s[8:9]
	global_store_dword v[96:97], v98, off sc1

; __device__ __forceinline__ unsigned cvt_pk_bf16(float lo, float hi) { unsigned r; asm volatile("v_cvt_pk_bf16_f32 %0, %1, %2" : "=v"(r) : "v"(lo), "v"(hi)); return r; }
;     __device__ __forceinline__ void operator()(const f32x4 (&acc)[2][2][4][2], const Unit& u, int wr, int wc, int fr, int fq) const {
;     ...
;                     sq += ((o0[0] * o0[0] + o0[1] * o0[1]) + (o0[2] * o0[2] + o0[3] * o0[3])) + ((o1[0] * o1[0] + o1[1] * o1[1]) + (o1[2] * o1[2] + o1[3] * o1[3]));
;                     if (hb) { const f32x4 y0 = o0 * wv[bj][0], y1 = o1 * wv[bj][1]; u32x4 z; z.x = cvt_pk_bf16(y0[0], y0[1]); z.y = cvt_pk_bf16(y0[2], y0[3]); z.z = cvt_pk_bf16(y1[0], y1[1]); z.w = cvt_pk_bf16(y1[2], y1[3]);
;                         *(u32x4*)(hb + (size_t)rowt * DM + off + bj * HALF) = z; } }
;                 if (ssq) { sq += __shfl_xor(sq, 16); sq += __shfl_xor(sq, 32); if (fq == 0) ssq[(size_t)(rowt + rl) * 16 + u.pn * 4 + wc] = sq; } }
.LBB0_1898:
	v_mul_f32_e32 v93, v93, v93
	v_mul_f32_e32 v89, v89, v89
	v_mul_f32_e32 v85, v85, v85
	v_mul_f32_e32 v81, v81, v81
	v_fmac_f32_e32 v93, v92, v92
	v_mul_f32_e32 v92, v95, v95
	v_fmac_f32_e32 v89, v88, v88
	v_mul_f32_e32 v88, v91, v91
	v_fmac_f32_e32 v85, v84, v84
	v_mul_f32_e32 v84, v87, v87
	v_fmac_f32_e32 v81, v80, v80
	v_mul_f32_e32 v80, v83, v83
	v_fmac_f32_e32 v92, v94, v94
	v_fmac_f32_e32 v88, v90, v90
	v_fmac_f32_e32 v84, v86, v86
	v_fmac_f32_e32 v80, v82, v82
	v_add_f32_e32 v92, v93, v92
	v_add_f32_e32 v88, v89, v88
	v_add_f32_e32 v84, v85, v84
	v_add_f32_e32 v80, v81, v80
	v_add_f32_e32 v88, v92, v88
	v_add_f32_e32 v80, v84, v80
	v_add_f32_e32 v80, v88, v80
	ds_bpermute_b32 v81, v130, v80
	s_waitcnt lgkmcnt(0)
	v_add_f32_e32 v80, v80, v81
	ds_bpermute_b32 v81, v131, v80
	s_and_saveexec_b64 s[58:59], s[42:43]
	s_cbranch_execz .LBB0_1900
	s_waitcnt lgkmcnt(0)
	v_add_f32_e32 v82, v80, v81
	v_add_u32_e32 v80, s48, v204
	v_ashrrev_i32_e32 v81, 31, v80
	s_lshl_b32 s52, s0, 2
	v_lshlrev_b64 v[80:81], 6, v[80:81]
	s_ashr_i32 s53, s52, 31
	v_lshl_add_u64 v[80:81], s[14:15], 0, v[80:81]
	v_lshl_add_u64 v[80:81], s[52:53], 2, v[80:81]
	s_lshl_b32 s8, s69, 2
	v_lshl_add_u64 v[80:81], v[80:81], 0, s[8:9]
	global_store_dword v[80:81], v82, off sc1

; __device__ __forceinline__ unsigned cvt_pk_bf16(float lo, float hi) { unsigned r; asm volatile("v_cvt_pk_bf16_f32 %0, %1, %2" : "=v"(r) : "v"(lo), "v"(hi)); return r; }
;     __device__ __forceinline__ void operator()(const f32x4 (&acc)[2][2][4][2], const Unit& u, int wr, int wc, int fr, int fq) const {
;     ...
;                     sq += ((o0[0] * o0[0] + o0[1] * o0[1]) + (o0[2] * o0[2] + o0[3] * o0[3])) + ((o1[0] * o1[0] + o1[1] * o1[1]) + (o1[2] * o1[2] + o1[3] * o1[3]));
;                     if (hb) { const f32x4 y0 = o0 * wv[bj][0], y1 = o1 * wv[bj][1]; u32x4 z; z.x = cvt_pk_bf16(y0[0], y0[1]); z.y = cvt_pk_bf16(y0[2], y0[3]); z.z = cvt_pk_bf16(y1[0], y1[1]); z.w = cvt_pk_bf16(y1[2], y1[3]);
;                         *(u32x4*)(hb + (size_t)rowt * DM + off + bj * HALF) = z; } }
;                 if (ssq) { sq += __shfl_xor(sq, 16); sq += __shfl_xor(sq, 32); if (fq == 0) ssq[(size_t)(rowt + rl) * 16 + u.pn * 4 + wc] = sq; } }
.LBB0_1904:
	v_mul_f32_e32 v61, v61, v61
	v_mul_f32_e32 v57, v57, v57
	v_mul_f32_e32 v53, v53, v53
	v_mul_f32_e32 v49, v49, v49
	v_fmac_f32_e32 v61, v60, v60
	v_mul_f32_e32 v60, v63, v63
	v_fmac_f32_e32 v57, v56, v56
	v_mul_f32_e32 v56, v59, v59
	v_fmac_f32_e32 v53, v52, v52
	v_mul_f32_e32 v52, v55, v55
	v_fmac_f32_e32 v49, v48, v48
	v_mul_f32_e32 v48, v51, v51
	v_fmac_f32_e32 v60, v62, v62
	v_fmac_f32_e32 v56, v58, v58
	v_fmac_f32_e32 v52, v54, v54
	v_fmac_f32_e32 v48, v50, v50
	v_add_f32_e32 v60, v61, v60
	v_add_f32_e32 v56, v57, v56
	v_add_f32_e32 v52, v53, v52
	v_add_f32_e32 v48, v49, v48
	v_add_f32_e32 v56, v60, v56
	v_add_f32_e32 v48, v52, v48
	v_add_f32_e32 v48, v48, v56
	ds_bpermute_b32 v49, v130, v48
	s_waitcnt lgkmcnt(0)
	v_add_f32_e32 v48, v48, v49
	ds_bpermute_b32 v49, v131, v48
	s_and_saveexec_b64 s[58:59], s[42:43]
	s_cbranch_execz .LBB0_1906
	s_waitcnt lgkmcnt(0)
	v_add_f32_e32 v50, v48, v49
	v_add_u32_e32 v48, s48, v120
	v_ashrrev_i32_e32 v49, 31, v48
	s_lshl_b32 s52, s0, 2
	v_lshlrev_b64 v[48:49], 6, v[48:49]
	s_ashr_i32 s53, s52, 31
	v_lshl_add_u64 v[48:49], s[14:15], 0, v[48:49]
	v_lshl_add_u64 v[48:49], s[52:53], 2, v[48:49]
	s_lshl_b32 s8, s69, 2
	v_lshl_add_u64 v[48:49], v[48:49], 0, s[8:9]
	global_store_dword v[48:49], v50, off sc1

; __device__ __forceinline__ unsigned cvt_pk_bf16(float lo, float hi) { unsigned r; asm volatile("v_cvt_pk_bf16_f32 %0, %1, %2" : "=v"(r) : "v"(lo), "v"(hi)); return r; }
;     __device__ __forceinline__ void operator()(const f32x4 (&acc)[2][2][4][2], const Unit& u, int wr, int wc, int fr, int fq) const {
;     ...
;                     sq += ((o0[0] * o0[0] + o0[1] * o0[1]) + (o0[2] * o0[2] + o0[3] * o0[3])) + ((o1[0] * o1[0] + o1[1] * o1[1]) + (o1[2] * o1[2] + o1[3] * o1[3]));
;                     if (hb) { const f32x4 y0 = o0 * wv[bj][0], y1 = o1 * wv[bj][1]; u32x4 z; z.x = cvt_pk_bf16(y0[0], y0[1]); z.y = cvt_pk_bf16(y0[2], y0[3]); z.z = cvt_pk_bf16(y1[0], y1[1]); z.w = cvt_pk_bf16(y1[2], y1[3]);
;                         *(u32x4*)(hb + (size_t)rowt * DM + off + bj * HALF) = z; } }
;                 if (ssq) { sq += __shfl_xor(sq, 16); sq += __shfl_xor(sq, 32); if (fq == 0) ssq[(size_t)(rowt + rl) * 16 + u.pn * 4 + wc] = sq; } }
.LBB0_1910:
	v_mul_f32_e32 v45, v45, v45
	v_mul_f32_e32 v41, v41, v41
	v_mul_f32_e32 v37, v37, v37
	v_mul_f32_e32 v33, v33, v33
	v_fmac_f32_e32 v45, v44, v44
	v_mul_f32_e32 v44, v47, v47
	v_fmac_f32_e32 v41, v40, v40
	v_mul_f32_e32 v40, v43, v43
	v_fmac_f32_e32 v37, v36, v36
	v_mul_f32_e32 v36, v39, v39
	v_fmac_f32_e32 v33, v32, v32
	v_mul_f32_e32 v32, v35, v35
	v_fmac_f32_e32 v44, v46, v46
	v_fmac_f32_e32 v40, v42, v42
	v_fmac_f32_e32 v36, v38, v38
	v_fmac_f32_e32 v32, v34, v34
	v_add_f32_e32 v44, v45, v44
	v_add_f32_e32 v40, v41, v40
	v_add_f32_e32 v36, v37, v36
	v_add_f32_e32 v32, v33, v32
	v_add_f32_e32 v40, v44, v40
	v_add_f32_e32 v32, v36, v32
	v_add_f32_e32 v32, v40, v32
	ds_bpermute_b32 v33, v130, v32
	s_waitcnt lgkmcnt(0)
	v_add_f32_e32 v32, v32, v33
	ds_bpermute_b32 v33, v131, v32
	s_and_saveexec_b64 s[58:59], s[42:43]
	s_cbranch_execz .LBB0_1912
	s_waitcnt lgkmcnt(0)
	v_add_f32_e32 v34, v32, v33
	v_add_u32_e32 v32, s48, v116
	v_ashrrev_i32_e32 v33, 31, v32
	s_lshl_b32 s52, s0, 2
	v_lshlrev_b64 v[32:33], 6, v[32:33]
	s_ashr_i32 s53, s52, 31
	v_lshl_add_u64 v[32:33], s[14:15], 0, v[32:33]
	v_lshl_add_u64 v[32:33], s[52:53], 2, v[32:33]
	s_lshl_b32 s8, s69, 2
	v_lshl_add_u64 v[32:33], v[32:33], 0, s[8:9]
	global_store_dword v[32:33], v34, off sc1

; __device__ __forceinline__ unsigned cvt_pk_bf16(float lo, float hi) { unsigned r; asm volatile("v_cvt_pk_bf16_f32 %0, %1, %2" : "=v"(r) : "v"(lo), "v"(hi)); return r; }
;     __device__ __forceinline__ void operator()(const f32x4 (&acc)[2][2][4][2], const Unit& u, int wr, int wc, int fr, int fq) const {
;     ...
;                     sq += ((o0[0] * o0[0] + o0[1] * o0[1]) + (o0[2] * o0[2] + o0[3] * o0[3])) + ((o1[0] * o1[0] + o1[1] * o1[1]) + (o1[2] * o1[2] + o1[3] * o1[3]));
;                     if (hb) { const f32x4 y0 = o0 * wv[bj][0], y1 = o1 * wv[bj][1]; u32x4 z; z.x = cvt_pk_bf16(y0[0], y0[1]); z.y = cvt_pk_bf16(y0[2], y0[3]); z.z = cvt_pk_bf16(y1[0], y1[1]); z.w = cvt_pk_bf16(y1[2], y1[3]);
;                         *(u32x4*)(hb + (size_t)rowt * DM + off + bj * HALF) = z; } }
;                 if (ssq) { sq += __shfl_xor(sq, 16); sq += __shfl_xor(sq, 32); if (fq == 0) ssq[(size_t)(rowt + rl) * 16 + u.pn * 4 + wc] = sq; } }
.LBB0_1916:
	v_mul_f32_e32 v29, v29, v29
	v_mul_f32_e32 v25, v25, v25
	v_mul_f32_e32 v21, v21, v21
	v_mul_f32_e32 v17, v17, v17
	v_fmac_f32_e32 v29, v28, v28
	v_mul_f32_e32 v28, v31, v31
	v_fmac_f32_e32 v25, v24, v24
	v_mul_f32_e32 v24, v27, v27
	v_fmac_f32_e32 v21, v20, v20
	v_mul_f32_e32 v20, v23, v23
	v_fmac_f32_e32 v17, v16, v16
	v_mul_f32_e32 v16, v19, v19
	v_fmac_f32_e32 v28, v30, v30
	v_fmac_f32_e32 v24, v26, v26
	v_fmac_f32_e32 v20, v22, v22
	v_fmac_f32_e32 v16, v18, v18
	v_add_f32_e32 v28, v29, v28
	v_add_f32_e32 v24, v25, v24
	v_add_f32_e32 v20, v21, v20
	v_add_f32_e32 v16, v17, v16
	v_add_f32_e32 v24, v28, v24
	v_add_f32_e32 v16, v20, v16
	v_add_f32_e32 v16, v24, v16
	ds_bpermute_b32 v17, v130, v16
	s_waitcnt lgkmcnt(0)
	v_add_f32_e32 v16, v16, v17
	ds_bpermute_b32 v17, v131, v16
	s_and_saveexec_b64 s[58:59], s[42:43]
	s_cbranch_execz .LBB0_1918
	s_waitcnt lgkmcnt(0)
	v_add_f32_e32 v18, v16, v17
	v_add_u32_e32 v16, s48, v112
	v_ashrrev_i32_e32 v17, 31, v16
	s_lshl_b32 s52, s0, 2
	v_lshlrev_b64 v[16:17], 6, v[16:17]
	s_ashr_i32 s53, s52, 31
	v_lshl_add_u64 v[16:17], s[14:15], 0, v[16:17]
	v_lshl_add_u64 v[16:17], s[52:53], 2, v[16:17]
	s_lshl_b32 s8, s69, 2
	v_lshl_add_u64 v[16:17], v[16:17], 0, s[8:9]
	global_store_dword v[16:17], v18, off sc1

; __device__ __forceinline__ unsigned cvt_pk_bf16(float lo, float hi) { unsigned r; asm volatile("v_cvt_pk_bf16_f32 %0, %1, %2" : "=v"(r) : "v"(lo), "v"(hi)); return r; }
;     __device__ __forceinline__ void operator()(const f32x4 (&acc)[2][2][4][2], const Unit& u, int wr, int wc, int fr, int fq) const {
;     ...
;                     sq += ((o0[0] * o0[0] + o0[1] * o0[1]) + (o0[2] * o0[2] + o0[3] * o0[3])) + ((o1[0] * o1[0] + o1[1] * o1[1]) + (o1[2] * o1[2] + o1[3] * o1[3]));
;                     if (hb) { const f32x4 y0 = o0 * wv[bj][0], y1 = o1 * wv[bj][1]; u32x4 z; z.x = cvt_pk_bf16(y0[0], y0[1]); z.y = cvt_pk_bf16(y0[2], y0[3]); z.z = cvt_pk_bf16(y1[0], y1[1]); z.w = cvt_pk_bf16(y1[2], y1[3]);
;                         *(u32x4*)(hb + (size_t)rowt * DM + off + bj * HALF) = z; } }
;                 if (ssq) { sq += __shfl_xor(sq, 16); sq += __shfl_xor(sq, 32); if (fq == 0) ssq[(size_t)(rowt + rl) * 16 + u.pn * 4 + wc] = sq; } }
.LBB0_1922:
	v_mul_f32_e32 v13, v13, v13
	v_mul_f32_e32 v9, v9, v9
	v_mul_f32_e32 v5, v5, v5
	v_mul_f32_e32 v1, v1, v1
	v_fmac_f32_e32 v13, v12, v12
	v_mul_f32_e32 v12, v15, v15
	v_fmac_f32_e32 v9, v8, v8
	v_mul_f32_e32 v8, v11, v11
	v_fmac_f32_e32 v5, v4, v4
	v_mul_f32_e32 v4, v7, v7
	v_fmac_f32_e32 v1, v0, v0
	v_mul_f32_e32 v0, v3, v3
	v_fmac_f32_e32 v12, v14, v14
	v_fmac_f32_e32 v8, v10, v10
	v_fmac_f32_e32 v4, v6, v6
	v_fmac_f32_e32 v0, v2, v2
	v_add_f32_e32 v12, v13, v12
	v_add_f32_e32 v8, v9, v8
	v_add_f32_e32 v4, v5, v4
	v_add_f32_e32 v0, v1, v0
	v_add_f32_e32 v8, v12, v8
	v_add_f32_e32 v0, v4, v0
	v_add_f32_e32 v0, v8, v0
	ds_bpermute_b32 v1, v130, v0
	s_waitcnt lgkmcnt(0)
	v_add_f32_e32 v0, v0, v1
	ds_bpermute_b32 v1, v131, v0
	s_and_saveexec_b64 s[40:41], s[42:43]
	s_cbranch_execz .LBB0_1924
	s_waitcnt lgkmcnt(0)
	v_add_f32_e32 v2, v0, v1
	v_add_u32_e32 v0, s48, v108
	v_ashrrev_i32_e32 v1, 31, v0
	s_lshl_b32 s0, s0, 2
	v_lshlrev_b64 v[0:1], 6, v[0:1]
	s_ashr_i32 s1, s0, 31
	v_lshl_add_u64 v[0:1], s[14:15], 0, v[0:1]
	v_lshl_add_u64 v[0:1], s[0:1], 2, v[0:1]
	s_lshl_b32 s8, s69, 2
	v_lshl_add_u64 v[0:1], v[0:1], 0, s[8:9]
	global_store_dword v[0:1], v2, off sc1

;     __device__ void init(int G_, int c_) { so.init(MLAT, DM, G_, c_); G = G_; c = c_; }
; #define LAS __attribute__((address_space(3)))
; #define CACC  WSP(float, WS_G)
; #define SSQ    WSP(float, WS_SSQ)
; #define PHASE_END   } if (ph + 1 < hi) { if (lo < 0) grid.sync(); int tb_ = tid0; asm volatile("" : "+v"(tb_)); xcd_barrier(xbar, tb_); if ((PROBE_MASK >> 8) & 1) xcd_barrier(xbar, tb_); } } ++ph;
; __global__ void __launch_bounds__(NWAVES * 64, 2) fwd_kernel(Args args) {
;     ...
;         PHASE_BEGIN
;         {
;             if (layer == 0) {
;                 pg8::Gemm g{FB, W2T, MALL, DM, DFF, DFF, 0, DFF}; pg8::SplitOrder S; S.init(G, bx);
;                 pg8::EpiResSplit E{{nullptr, nullptr, H16, modl + 5 * 1024, nullptr, AB, ng0 + 2 * DM, modl + 3 * 6144 + 1024, SSQ}, CACC};
;                 pg8::gemm_phase<pg8::EpiResSplit, pg8::SplitOrder>(L, g, S, E, tid);
;                 { const int fi = TAIL_FIRST(MLAT / 256 * 4 + 32);
;                   if (bx >= fi) { LAS float* scr = (LAS float*)(L + wave * 16640); TR_RUN(3, 3584, (bx - fi) * NWAVES + wave, (G - fi) * NWAVES);
;                       BIAS_RUN(16384, 18432, (bx - fi) * NWAVES + wave, (G - fi) * NWAVES); } }
;             } else {
;                 pg8::Gemm g{FB, W2T + (size_t)layer * DM * DFF, MLAT, DM, DFF, DFF, 0, DFF}; pg8::StaticOrder S; S.init(MLAT, DM, G, bx);
;                 pg8::EpiRes E{nullptr, nullptr, H16, modl + 5 * 1024, nullptr, next_hb ? AB : nullptr, ng0 + 2 * DM, modl + 3 * 6144 + 1024, SSQ};
;                 pg8::gemm_phase<pg8::EpiRes, pg8::StaticOrder>(L, g, S, E, tid);
;             }
;         }
;         PHASE_END
.Lgs_lb_157:
	s_getpc_b64 s[98:99]

.LBB0_2087:
	v_readlane_b32 s100, v255, 8
	s_cmp_eq_u32 s100, 1
	s_cbranch_scc0 .Lgs_orig_5
	s_waitcnt vmcnt(0) lgkmcnt(0)
	s_barrier
	v_readlane_b32 s100, v255, 59
	s_add_i32 s100, s100, 1
	v_writelane_b32 v255, s100, 59
	v_cmp_eq_u32_e32 vcc, 0, v215
	s_and_saveexec_b64 s[0:1], vcc
	s_cbranch_execz .Lgs_w_5
	s_load_dwordx2 s[2:3], s[94:95], 0xb8
	v_readlane_b32 s101, v255, 12
	s_and_b32 s101, s101, 63
	s_lshl_b32 s101, s101, 6
	s_cmp_lt_u32 s101, 0x800
	s_movk_i32 s7, 0x1400
	s_cselect_b32 s7, 0xc00, s7
	s_add_i32 s101, s101, s7
	s_lshl_b32 s100, s100, 2
	v_mov_b32_e32 v0, s101
	v_mov_b32_e32 v1, 1
	s_waitcnt lgkmcnt(0)
	s_add_u32 s2, s2, 0xe0000
	s_addc_u32 s3, s3, 0
	global_atomic_add v0, v1, s[2:3]
	buffer_inv sc1
	s_mov_b32 s6, 0
